# scan Y-blocks (hf0,q1)/(hf1,q0) QS+PV chains software-pipelined; B2 epilogue SS loads hoisted; S-update pipelined; bit-identical outputs
# baseline (speedup 1.0000x reference)
.LBB0_522:
	ds_read_b64 v[66:67], v165 offset:8192
	ds_read_b64 v[68:69], v166 offset:8192
	ds_read_b64 v[130:131], v167 offset:8192
	ds_read_b64 v[132:133], v168 offset:8192
	ds_read_b64 v[134:135], v169 offset:8192
	ds_read_b64 v[136:137], v170 offset:8192
	ds_read_b64 v[196:197], v171 offset:8192
	ds_read_b64 v[198:199], v172 offset:8192
	s_add_i32 s2, 0, 0x20400
	v_add_u32_e32 v219, s2, v164
	s_and_b64 vcc, exec, s[6:7]
	s_waitcnt lgkmcnt(6)
	v_mfma_f32_32x32x16_bf16 v[66:81], v[66:69], v[98:101], 0
	ds_read_b64 v[250:251], v173 offset:8192
	ds_read_b64 v[252:253], v174 offset:8192
	s_waitcnt lgkmcnt(6)
	v_mfma_f32_32x32x16_bf16 v[66:81], v[130:133], v[102:105], v[66:81]
	ds_read_b64 v[130:131], v175 offset:8192
	ds_read_b64 v[132:133], v176 offset:8192
	s_waitcnt lgkmcnt(6)
	v_mfma_f32_32x32x16_bf16 v[66:81], v[134:137], v[106:109], v[66:81]
	ds_read_b64 v[134:135], v178 offset:8192
	ds_read_b64 v[136:137], v179 offset:8192
	s_waitcnt lgkmcnt(6)
	v_mfma_f32_32x32x16_bf16 v[66:81], v[196:199], v[110:113], v[66:81]
	ds_read_b64 v[196:197], v180 offset:8192
	ds_read_b64 v[198:199], v181 offset:8192
	s_waitcnt lgkmcnt(6)
	v_mfma_f32_32x32x16_bf16 v[66:81], v[250:253], v[114:117], v[66:81]
	ds_read_b128 v[250:253], v219 offset:224
	s_waitcnt lgkmcnt(5)
	v_mfma_f32_32x32x16_bf16 v[66:81], v[130:133], v[118:121], v[66:81]
	ds_read_b128 v[130:133], v219 offset:128
	s_waitcnt lgkmcnt(4)
	v_mfma_f32_32x32x16_bf16 v[66:81], v[134:137], v[122:125], v[66:81]
	ds_read_b128 v[134:137], v219 offset:160
	s_waitcnt lgkmcnt(3)
	v_mfma_f32_32x32x16_bf16 v[66:81], v[196:199], v[126:129], v[66:81]
	ds_read_b128 v[196:199], v219 offset:192
	s_waitcnt lgkmcnt(2)
	s_nop 9
	v_pk_mul_f32 v[78:79], v[78:79], v[250:251]
	v_pk_mul_f32 v[80:81], v[80:81], v[252:253]
	v_pk_mul_f32 v[66:67], v[66:67], v[130:131]
	v_pk_mul_f32 v[68:69], v[68:69], v[132:133]
	ds_read_b64_tr_b16 v[130:131], v159
	ds_read_b64_tr_b16 v[132:133], v158 offset:1024
	ds_read_b128 v[250:253], v187 offset:8192
	s_waitcnt lgkmcnt(3)
	v_pk_mul_f32 v[70:71], v[70:71], v[134:135]
	v_pk_mul_f32 v[72:73], v[72:73], v[136:137]
	v_pk_mul_f32 v[74:75], v[74:75], v[196:197]
	v_pk_mul_f32 v[76:77], v[76:77], v[198:199]
	ds_read_b64_tr_b16 v[134:135], v159 offset:4096
	ds_read_b64_tr_b16 v[136:137], v158 offset:5120
	ds_read_b128 v[196:199], v188 offset:8192
	s_waitcnt lgkmcnt(3)
	v_mfma_f32_32x32x16_bf16 v[66:81], v[250:253], v[130:133], v[66:81]
	ds_read_b64_tr_b16 v[130:131], v159 offset:8192
	ds_read_b64_tr_b16 v[132:133], v158 offset:9216
	ds_read_b128 v[250:253], v189 offset:8192
	s_waitcnt lgkmcnt(3)
	v_mfma_f32_32x32x16_bf16 v[66:81], v[196:199], v[134:137], v[66:81]
	ds_read_b64_tr_b16 v[134:135], v159 offset:12288
	ds_read_b64_tr_b16 v[136:137], v158 offset:13312
	ds_read_b128 v[196:199], v183 offset:8192
	s_waitcnt lgkmcnt(3)
	v_mfma_f32_32x32x16_bf16 v[66:81], v[250:253], v[130:133], v[66:81]
	ds_read_b64_tr_b16 v[130:131], v159 offset:16384
	ds_read_b64_tr_b16 v[132:133], v158 offset:17408
	ds_read_b128 v[250:253], v182 offset:8192
	s_waitcnt lgkmcnt(3)
	v_mfma_f32_32x32x16_bf16 v[66:81], v[196:199], v[134:137], v[66:81]
	ds_read_b64_tr_b16 v[134:135], v159 offset:20480
	ds_read_b64_tr_b16 v[136:137], v158 offset:21504
	ds_read_b128 v[196:199], v184 offset:8192
	s_waitcnt lgkmcnt(3)
	v_mfma_f32_32x32x16_bf16 v[66:81], v[250:253], v[130:133], v[66:81]
	ds_read_b64_tr_b16 v[130:131], v159 offset:24576
	ds_read_b64_tr_b16 v[132:133], v158 offset:25600
	ds_read_b128 v[250:253], v185 offset:8192
	s_waitcnt lgkmcnt(3)
	v_mfma_f32_32x32x16_bf16 v[66:81], v[196:199], v[134:137], v[66:81]
	ds_read_b64_tr_b16 v[134:135], v159 offset:28672
	ds_read_b64_tr_b16 v[136:137], v158 offset:29696
	ds_read_b128 v[196:199], v186 offset:8192
	s_waitcnt lgkmcnt(3)
	v_mfma_f32_32x32x16_bf16 v[66:81], v[250:253], v[130:133], v[66:81]
	s_waitcnt lgkmcnt(0)
	v_mfma_f32_32x32x16_bf16 v[66:81], v[196:199], v[134:137], v[66:81]
	s_cbranch_vccnz .LBB0_524
	s_add_i32 s2, 0, 0x20a00
	v_add_u32_e32 v145, s2, v164
	ds_read_b128 v[130:133], v145 offset:224
	ds_read_b128 v[134:137], v145 offset:192
	ds_read_b128 v[196:199], v145 offset:160
	ds_read_b128 v[250:253], v145 offset:128
	s_waitcnt lgkmcnt(3)
	s_nop 3
	v_pk_mul_f32 v[78:79], v[78:79], v[130:131]
	s_waitcnt lgkmcnt(2)
	v_pk_mul_f32 v[74:75], v[74:75], v[134:135]
	s_waitcnt lgkmcnt(1)
	v_pk_mul_f32 v[70:71], v[70:71], v[196:197]
	v_pk_mul_f32 v[80:81], v[80:81], v[132:133]
	v_pk_mul_f32 v[76:77], v[76:77], v[136:137]
	v_pk_mul_f32 v[72:73], v[72:73], v[198:199]
	s_waitcnt lgkmcnt(0)
	v_pk_mul_f32 v[68:69], v[68:69], v[252:253]
	v_pk_mul_f32 v[66:67], v[66:67], v[250:251]

.LBB0_546:
	ds_read_b64 v[66:67], v165 offset:16384
	ds_read_b64 v[68:69], v166 offset:16384
	ds_read_b64 v[132:133], v167 offset:16384
	ds_read_b64 v[134:135], v168 offset:16384
	ds_read_b64 v[146:147], v169 offset:16384
	ds_read_b64 v[148:149], v170 offset:16384
	ds_read_b64 v[196:197], v171 offset:16384
	ds_read_b64 v[198:199], v172 offset:16384
	s_and_b64 vcc, exec, s[6:7]
	s_waitcnt lgkmcnt(6)
	v_mfma_f32_32x32x16_bf16 v[66:81], v[66:69], v[98:101], 0
	ds_read_b64 v[200:201], v173 offset:16384
	ds_read_b64 v[202:203], v174 offset:16384
	s_waitcnt lgkmcnt(6)
	v_mfma_f32_32x32x16_bf16 v[66:81], v[132:135], v[102:105], v[66:81]
	ds_read_b64 v[132:133], v175 offset:16384
	ds_read_b64 v[134:135], v176 offset:16384
	s_waitcnt lgkmcnt(6)
	v_mfma_f32_32x32x16_bf16 v[66:81], v[146:149], v[106:109], v[66:81]
	ds_read_b64 v[146:147], v178 offset:16384
	ds_read_b64 v[148:149], v179 offset:16384
	s_waitcnt lgkmcnt(6)
	v_mfma_f32_32x32x16_bf16 v[66:81], v[196:199], v[110:113], v[66:81]
	ds_read_b64 v[196:197], v180 offset:16384
	ds_read_b64 v[198:199], v181 offset:16384
	s_waitcnt lgkmcnt(6)
	v_mfma_f32_32x32x16_bf16 v[66:81], v[200:203], v[114:117], v[66:81]
	ds_read_b128 v[200:203], v219 offset:352
	s_waitcnt lgkmcnt(5)
	v_mfma_f32_32x32x16_bf16 v[66:81], v[132:135], v[118:121], v[66:81]
	ds_read_b128 v[132:135], v219 offset:256
	s_waitcnt lgkmcnt(4)
	v_mfma_f32_32x32x16_bf16 v[66:81], v[146:149], v[122:125], v[66:81]
	ds_read_b128 v[146:149], v219 offset:288
	s_waitcnt lgkmcnt(3)
	v_mfma_f32_32x32x16_bf16 v[66:81], v[196:199], v[126:129], v[66:81]
	ds_read_b128 v[196:199], v219 offset:320
	s_waitcnt lgkmcnt(2)
	s_nop 9
	v_pk_mul_f32 v[78:79], v[78:79], v[200:201]
	v_pk_mul_f32 v[80:81], v[80:81], v[202:203]
	v_pk_mul_f32 v[66:67], v[66:67], v[132:133]
	v_pk_mul_f32 v[68:69], v[68:69], v[134:135]
	ds_read_b64_tr_b16 v[132:133], v159
	ds_read_b64_tr_b16 v[134:135], v158 offset:1024
	ds_read_b128 v[200:203], v187
	s_waitcnt lgkmcnt(3)
	v_pk_mul_f32 v[70:71], v[70:71], v[146:147]
	v_pk_mul_f32 v[72:73], v[72:73], v[148:149]
	v_pk_mul_f32 v[74:75], v[74:75], v[196:197]
	v_pk_mul_f32 v[76:77], v[76:77], v[198:199]
	ds_read_b64_tr_b16 v[146:147], v159 offset:4096
	ds_read_b64_tr_b16 v[148:149], v158 offset:5120
	ds_read_b128 v[196:199], v188
	s_waitcnt lgkmcnt(3)
	v_mfma_f32_32x32x16_bf16 v[66:81], v[200:203], v[132:135], v[66:81]
	ds_read_b64_tr_b16 v[132:133], v159 offset:8192
	ds_read_b64_tr_b16 v[134:135], v158 offset:9216
	ds_read_b128 v[200:203], v189
	s_waitcnt lgkmcnt(3)
	v_mfma_f32_32x32x16_bf16 v[66:81], v[196:199], v[146:149], v[66:81]
	ds_read_b64_tr_b16 v[146:147], v159 offset:12288
	ds_read_b64_tr_b16 v[148:149], v158 offset:13312
	ds_read_b128 v[196:199], v183
	s_waitcnt lgkmcnt(3)
	v_mfma_f32_32x32x16_bf16 v[66:81], v[200:203], v[132:135], v[66:81]
	ds_read_b64_tr_b16 v[132:133], v159 offset:16384
	ds_read_b64_tr_b16 v[134:135], v158 offset:17408
	ds_read_b128 v[200:203], v182
	s_waitcnt lgkmcnt(3)
	v_mfma_f32_32x32x16_bf16 v[66:81], v[196:199], v[146:149], v[66:81]
	ds_read_b64_tr_b16 v[146:147], v159 offset:20480
	ds_read_b64_tr_b16 v[148:149], v158 offset:21504
	ds_read_b128 v[196:199], v184
	s_waitcnt lgkmcnt(3)
	v_mfma_f32_32x32x16_bf16 v[66:81], v[200:203], v[132:135], v[66:81]
	ds_read_b64_tr_b16 v[132:133], v159 offset:24576
	ds_read_b64_tr_b16 v[134:135], v158 offset:25600
	ds_read_b128 v[200:203], v185
	s_waitcnt lgkmcnt(3)
	v_mfma_f32_32x32x16_bf16 v[66:81], v[196:199], v[146:149], v[66:81]
	ds_read_b64_tr_b16 v[146:147], v159 offset:28672
	ds_read_b64_tr_b16 v[148:149], v158 offset:29696
	ds_read_b128 v[196:199], v186
	s_waitcnt lgkmcnt(3)
	v_mfma_f32_32x32x16_bf16 v[66:81], v[200:203], v[132:135], v[66:81]
	s_waitcnt lgkmcnt(0)
	v_mfma_f32_32x32x16_bf16 v[66:81], v[196:199], v[146:149], v[66:81]
	s_cbranch_vccz .LBB0_560
	s_and_b64 vcc, exec, s[14:15]
	s_mov_b64 s[10:11], -1
	s_cbranch_vccz .LBB0_561

.LBB0_678:
	s_ashr_i32 s11, s16, 3
	s_lshl_b32 s18, s11, 11
	s_ashr_i32 s19, s18, 31
	s_and_b32 s9, s16, 7
	s_lshl_b32 s20, s11, 1
	s_lshl_b64 s[18:19], s[18:19], 2
	v_lshl_or_b32 v146, s9, 8, v215
	s_add_u32 s18, s36, s18
	s_addc_u32 s19, s37, s19
	v_lshlrev_b32_e32 v134, 2, v146
	s_mul_i32 s11, s11, 0x11000000
	global_load_dwordx4 v[138:141], v134, s[18:19] offset:16
	global_load_dwordx4 v[142:145], v134, s[18:19]
	global_load_dwordx4 v[130:133], v134, s[18:19] offset:528
	s_nop 0
	global_load_dwordx4 v[134:137], v134, s[18:19] offset:512
	s_mul_hi_i32 s18, s20, 0x8800000
	s_add_u32 s20, s69, s11
	s_addc_u32 s21, s77, s18
	v_lshlrev_b32_e32 v190, 1, v146
	v_lshl_add_u64 v[200:201], s[20:21], 0, v[190:191]
	v_lshlrev_b64 v[204:205], 12, v[186:187]
	v_lshl_add_u64 v[146:147], v[200:201], 0, v[204:205]
	v_lshlrev_b64 v[202:203], 12, v[188:189]
	global_load_dwordx4 v[158:161], v[146:147], off
	global_load_dwordx4 v[154:157], v[146:147], off offset:256
	v_lshl_add_u64 v[146:147], v[200:201], 0, v[202:203]
	global_load_dwordx4 v[150:153], v[146:147], off
	s_nop 0
	global_load_dwordx4 v[146:149], v[146:147], off offset:256
	v_pk_mul_f32 v[162:163], v[126:127], s[64:65] op_sel_hi:[1,0]
	s_cmp_lt_u32 s16, 8
	v_exp_f32_e32 v162, v162
	v_exp_f32_e32 v163, v163
	s_mov_b64 s[22:23], -1
	v_pk_add_f32 v[162:163], v[162:163], 1.0 op_sel_hi:[1,0]
	s_nop 0
	v_rcp_f32_e32 v206, v162
	v_rcp_f32_e32 v207, v163
	s_waitcnt vmcnt(0)
	v_lshlrev_b32_e32 v208, 16, v158
	v_and_b32_e32 v209, 0xffff0000, v158
	s_cbranch_scc1 .LBB0_680
	s_mul_i32 s18, s16, 0x22000
	v_readlane_b32 s19, v254, 54
	s_mul_hi_i32 s11, s16, 0x22000
	s_add_u32 s18, s19, s18
	v_readlane_b32 s19, v254, 55
	s_addc_u32 s19, s19, s11
	v_pk_mul_f32 v[166:167], v[128:129], s[64:65] op_sel_hi:[1,0]
	v_lshl_add_u64 v[210:211], v[186:187], 2, s[18:19]
	global_load_dword v158, v[210:211], off
	global_load_dword v170, v[210:211], off offset:64
	global_load_dword v238, v[210:211], off offset:128
	global_load_dword v239, v[210:211], off offset:192
	global_load_dword v240, v[210:211], off offset:512
	global_load_dword v241, v[210:211], off offset:576
	global_load_dword v242, v[210:211], off offset:640
	global_load_dword v243, v[210:211], off offset:704
	v_exp_f32_e32 v166, v166
	v_exp_f32_e32 v167, v167
	v_pk_mul_f32 v[164:165], v[206:207], v[142:143]
	v_pk_mul_f32 v[168:169], v[124:125], s[64:65] op_sel_hi:[1,0]
	v_pk_mul_f32 v[172:173], v[116:117], s[64:65] op_sel_hi:[1,0]
	v_pk_add_f32 v[166:167], v[166:167], 1.0 op_sel_hi:[1,0]
	v_exp_f32_e32 v168, v168
	v_rcp_f32_e32 v166, v166
	v_rcp_f32_e32 v167, v167
	v_exp_f32_e32 v169, v169
	v_exp_f32_e32 v172, v172
	v_exp_f32_e32 v173, v173
	v_pk_mul_f32 v[166:167], v[166:167], v[144:145]
	v_pk_add_f32 v[168:169], v[168:169], 1.0 op_sel_hi:[1,0]
	v_pk_mul_f32 v[222:223], v[94:95], s[64:65] op_sel_hi:[1,0]
	v_rcp_f32_e32 v168, v168
	v_rcp_f32_e32 v169, v169
	v_pk_add_f32 v[172:173], v[172:173], 1.0 op_sel_hi:[1,0]
	v_exp_f32_e32 v222, v222
	v_rcp_f32_e32 v172, v172
	v_pk_mul_f32 v[168:169], v[168:169], v[140:141]
	v_rcp_f32_e32 v173, v173
	v_exp_f32_e32 v223, v223
	s_mov_b64 s[22:23], 0
	v_pk_mul_f32 v[172:173], v[172:173], v[132:133]
	v_pk_add_f32 v[222:223], v[222:223], 1.0 op_sel_hi:[1,0]
	s_waitcnt vmcnt(7)
	v_fmamk_f32 v158, v158, 0x3b800000, v229
	v_rsq_f32_e32 v158, v158
	v_rcp_f32_e32 v222, v222
	v_rcp_f32_e32 v223, v223
	v_pk_mul_f32 v[162:163], v[158:159], v[208:209] op_sel_hi:[0,1]
	v_pk_mul_f32 v[162:163], v[164:165], v[162:163]
	v_lshlrev_b32_e32 v164, 16, v159
	v_and_b32_e32 v165, 0xffff0000, v159
	v_pk_mul_f32 v[164:165], v[158:159], v[164:165] op_sel_hi:[0,1]
	v_pk_mul_f32 v[164:165], v[166:167], v[164:165]
	v_pk_mul_f32 v[166:167], v[122:123], s[64:65] op_sel_hi:[1,0]
	v_cvt_pk_bf16_f32 v162, v162, v163
	v_exp_f32_e32 v166, v166
	v_exp_f32_e32 v167, v167
	v_cvt_pk_bf16_f32 v163, v164, v165
	v_lshlrev_b32_e32 v164, 16, v160
	v_and_b32_e32 v165, 0xffff0000, v160
	v_pk_add_f32 v[166:167], v[166:167], 1.0 op_sel_hi:[1,0]
	v_pk_mul_f32 v[164:165], v[158:159], v[164:165] op_sel_hi:[0,1]
	v_rcp_f32_e32 v166, v166
	v_rcp_f32_e32 v167, v167
	v_pk_mul_f32 v[222:223], v[222:223], v[142:143]
	v_pk_mul_f32 v[166:167], v[166:167], v[138:139]
	s_nop 0
	v_pk_mul_f32 v[164:165], v[166:167], v[164:165]
	v_lshlrev_b32_e32 v166, 16, v161
	v_and_b32_e32 v167, 0xffff0000, v161
	v_pk_mul_f32 v[166:167], v[158:159], v[166:167] op_sel_hi:[0,1]
	v_pk_mul_f32 v[166:167], v[168:169], v[166:167]
	v_cvt_pk_bf16_f32 v164, v164, v165
	v_cvt_pk_bf16_f32 v165, v166, v167
	v_lshl_add_u64 v[166:167], s[20:21], 0, v[204:205]
	v_lshl_add_u64 v[166:167], v[166:167], 0, v[190:191]
	global_store_dwordx4 v[166:167], v[162:165], off
	v_pk_mul_f32 v[168:169], v[120:121], s[64:65] op_sel_hi:[1,0]
	s_nop 0
	v_pk_mul_f32 v[164:165], v[118:119], s[64:65] op_sel_hi:[1,0]
	v_exp_f32_e32 v168, v168
	v_exp_f32_e32 v164, v164
	v_exp_f32_e32 v165, v165
	v_exp_f32_e32 v169, v169
	v_lshlrev_b32_e32 v162, 16, v154
	v_and_b32_e32 v163, 0xffff0000, v154
	v_pk_add_f32 v[164:165], v[164:165], 1.0 op_sel_hi:[1,0]
	v_pk_add_f32 v[168:169], v[168:169], 1.0 op_sel_hi:[1,0]
	v_rcp_f32_e32 v164, v164
	v_rcp_f32_e32 v165, v165
	v_rcp_f32_e32 v168, v168
	v_rcp_f32_e32 v169, v169
	v_pk_mul_f32 v[162:163], v[158:159], v[162:163] op_sel_hi:[0,1]
	v_pk_mul_f32 v[164:165], v[164:165], v[134:135]
	v_pk_mul_f32 v[168:169], v[168:169], v[136:137]
	v_pk_mul_f32 v[162:163], v[164:165], v[162:163]
	v_lshlrev_b32_e32 v164, 16, v155
	v_and_b32_e32 v165, 0xffff0000, v155
	v_pk_mul_f32 v[164:165], v[158:159], v[164:165] op_sel_hi:[0,1]
	v_pk_mul_f32 v[164:165], v[168:169], v[164:165]
	v_pk_mul_f32 v[168:169], v[114:115], s[64:65] op_sel_hi:[1,0]
	v_cvt_pk_bf16_f32 v162, v162, v163
	v_exp_f32_e32 v168, v168
	v_exp_f32_e32 v169, v169
	v_cvt_pk_bf16_f32 v163, v164, v165
	v_lshlrev_b32_e32 v164, 16, v156
	v_and_b32_e32 v165, 0xffff0000, v156
	v_pk_add_f32 v[168:169], v[168:169], 1.0 op_sel_hi:[1,0]
	v_pk_mul_f32 v[164:165], v[158:159], v[164:165] op_sel_hi:[0,1]
	v_rcp_f32_e32 v168, v168
	v_rcp_f32_e32 v169, v169
	s_nop 0
	v_pk_mul_f32 v[168:169], v[168:169], v[130:131]
	s_nop 0
	v_pk_mul_f32 v[164:165], v[168:169], v[164:165]
	v_lshlrev_b32_e32 v168, 16, v157
	v_and_b32_e32 v169, 0xffff0000, v157
	v_pk_mul_f32 v[168:169], v[158:159], v[168:169] op_sel_hi:[0,1]
	v_pk_mul_f32 v[168:169], v[172:173], v[168:169]
	v_cvt_pk_bf16_f32 v164, v164, v165
	v_cvt_pk_bf16_f32 v165, v168, v169
	global_store_dwordx4 v[166:167], v[162:165], off offset:256
	v_pk_mul_f32 v[166:167], v[112:113], s[64:65] op_sel_hi:[1,0]
	s_waitcnt vmcnt(8)
	v_fmamk_f32 v158, v170, 0x3b800000, v229
	v_pk_mul_f32 v[164:165], v[110:111], s[64:65] op_sel_hi:[1,0]
	v_exp_f32_e32 v166, v166
	v_exp_f32_e32 v164, v164
	v_exp_f32_e32 v165, v165
	v_exp_f32_e32 v167, v167
	v_rsq_f32_e32 v158, v158
	v_lshlrev_b32_e32 v162, 16, v150
	v_pk_add_f32 v[164:165], v[164:165], 1.0 op_sel_hi:[1,0]
	v_pk_add_f32 v[166:167], v[166:167], 1.0 op_sel_hi:[1,0]
	v_rcp_f32_e32 v164, v164
	v_rcp_f32_e32 v165, v165
	v_rcp_f32_e32 v166, v166
	v_rcp_f32_e32 v167, v167
	v_and_b32_e32 v163, 0xffff0000, v150
	v_pk_mul_f32 v[162:163], v[158:159], v[162:163] op_sel_hi:[0,1]
	v_pk_mul_f32 v[164:165], v[164:165], v[142:143]
	v_pk_mul_f32 v[166:167], v[166:167], v[144:145]
	v_pk_mul_f32 v[162:163], v[164:165], v[162:163]
	v_lshlrev_b32_e32 v164, 16, v151
	v_and_b32_e32 v165, 0xffff0000, v151
	v_pk_mul_f32 v[164:165], v[158:159], v[164:165] op_sel_hi:[0,1]
	v_pk_mul_f32 v[164:165], v[166:167], v[164:165]
	v_pk_mul_f32 v[166:167], v[106:107], s[64:65] op_sel_hi:[1,0]
	v_pk_mul_f32 v[168:169], v[108:109], s[64:65] op_sel_hi:[1,0]
	v_exp_f32_e32 v166, v166
	v_exp_f32_e32 v167, v167
	v_exp_f32_e32 v168, v168
	v_exp_f32_e32 v169, v169
	v_cvt_pk_bf16_f32 v162, v162, v163
	v_pk_add_f32 v[166:167], v[166:167], 1.0 op_sel_hi:[1,0]
	v_cvt_pk_bf16_f32 v163, v164, v165
	v_rcp_f32_e32 v166, v166
	v_rcp_f32_e32 v167, v167
	v_pk_add_f32 v[168:169], v[168:169], 1.0 op_sel_hi:[1,0]
	v_lshlrev_b32_e32 v164, 16, v152
	v_rcp_f32_e32 v168, v168
	v_rcp_f32_e32 v169, v169
	v_and_b32_e32 v165, 0xffff0000, v152
	v_pk_mul_f32 v[164:165], v[158:159], v[164:165] op_sel_hi:[0,1]
	v_pk_mul_f32 v[166:167], v[166:167], v[138:139]
	v_pk_mul_f32 v[168:169], v[168:169], v[140:141]
	v_pk_mul_f32 v[164:165], v[166:167], v[164:165]
	v_lshlrev_b32_e32 v166, 16, v153
	v_and_b32_e32 v167, 0xffff0000, v153
	v_pk_mul_f32 v[166:167], v[158:159], v[166:167] op_sel_hi:[0,1]
	v_pk_mul_f32 v[166:167], v[168:169], v[166:167]
	v_cvt_pk_bf16_f32 v164, v164, v165
	v_cvt_pk_bf16_f32 v165, v166, v167
	v_lshl_add_u64 v[166:167], s[20:21], 0, v[202:203]
	v_lshl_add_u64 v[166:167], v[166:167], 0, v[190:191]
	global_store_dwordx4 v[166:167], v[162:165], off
	v_pk_mul_f32 v[168:169], v[104:105], s[64:65] op_sel_hi:[1,0]
	v_pk_mul_f32 v[170:171], v[100:101], s[64:65] op_sel_hi:[1,0]
	v_pk_mul_f32 v[164:165], v[102:103], s[64:65] op_sel_hi:[1,0]
	v_exp_f32_e32 v168, v168
	v_exp_f32_e32 v164, v164
	v_exp_f32_e32 v165, v165
	v_exp_f32_e32 v169, v169
	v_lshlrev_b32_e32 v162, 16, v146
	v_and_b32_e32 v163, 0xffff0000, v146
	v_pk_add_f32 v[164:165], v[164:165], 1.0 op_sel_hi:[1,0]
	v_pk_add_f32 v[168:169], v[168:169], 1.0 op_sel_hi:[1,0]
	v_rcp_f32_e32 v164, v164
	v_rcp_f32_e32 v165, v165
	v_rcp_f32_e32 v168, v168
	v_rcp_f32_e32 v169, v169
	v_pk_mul_f32 v[162:163], v[158:159], v[162:163] op_sel_hi:[0,1]
	v_pk_mul_f32 v[164:165], v[164:165], v[134:135]
	v_exp_f32_e32 v170, v170
	v_pk_mul_f32 v[162:163], v[164:165], v[162:163]
	v_lshlrev_b32_e32 v164, 16, v147
	v_and_b32_e32 v165, 0xffff0000, v147
	v_pk_mul_f32 v[164:165], v[158:159], v[164:165] op_sel_hi:[0,1]
	v_pk_mul_f32 v[168:169], v[168:169], v[136:137]
	v_exp_f32_e32 v171, v171
	v_pk_mul_f32 v[164:165], v[168:169], v[164:165]
	v_pk_mul_f32 v[168:169], v[98:99], s[64:65] op_sel_hi:[1,0]
	v_cvt_pk_bf16_f32 v162, v162, v163
	v_exp_f32_e32 v168, v168
	v_exp_f32_e32 v169, v169
	v_pk_add_f32 v[170:171], v[170:171], 1.0 op_sel_hi:[1,0]
	v_cvt_pk_bf16_f32 v163, v164, v165
	v_rcp_f32_e32 v170, v170
	v_pk_add_f32 v[168:169], v[168:169], 1.0 op_sel_hi:[1,0]
	v_rcp_f32_e32 v171, v171
	v_rcp_f32_e32 v168, v168
	v_rcp_f32_e32 v169, v169
	v_lshlrev_b32_e32 v164, 16, v148
	v_and_b32_e32 v165, 0xffff0000, v148
	v_pk_mul_f32 v[164:165], v[158:159], v[164:165] op_sel_hi:[0,1]
	v_pk_mul_f32 v[168:169], v[168:169], v[130:131]
	v_pk_mul_f32 v[170:171], v[170:171], v[132:133]
	v_pk_mul_f32 v[164:165], v[168:169], v[164:165]
	v_lshlrev_b32_e32 v168, 16, v149
	v_and_b32_e32 v169, 0xffff0000, v149
	v_pk_mul_f32 v[168:169], v[158:159], v[168:169] op_sel_hi:[0,1]
	v_pk_mul_f32 v[168:169], v[170:171], v[168:169]
	v_cvt_pk_bf16_f32 v164, v164, v165
	v_cvt_pk_bf16_f32 v165, v168, v169
	global_store_dwordx4 v[166:167], v[162:165], off offset:256
	s_waitcnt vmcnt(4)
	v_fmamk_f32 v158, v238, 0x3b800000, v229
	v_or_b32_e32 v162, 32, v186
	v_ashrrev_i32_e32 v163, 31, v162
	v_lshlrev_b64 v[218:219], 12, v[162:163]
	v_lshl_add_u64 v[162:163], v[200:201], 0, v[218:219]
	global_load_dwordx4 v[196:199], v[162:163], off
	global_load_dwordx4 v[170:173], v[162:163], off offset:256
	v_rsq_f32_e32 v158, v158
	v_or_b32_e32 v162, 48, v186
	v_ashrrev_i32_e32 v163, 31, v162
	v_lshlrev_b64 v[212:213], 12, v[162:163]
	v_lshl_add_u64 v[162:163], v[200:201], 0, v[212:213]
	global_load_dwordx4 v[166:169], v[162:163], off
	s_nop 0
	global_load_dwordx4 v[162:165], v[162:163], off offset:256
	v_lshl_add_u64 v[218:219], s[20:21], 0, v[218:219]
	v_lshl_add_u64 v[218:219], v[218:219], 0, v[190:191]
	s_waitcnt vmcnt(3)
	v_lshlrev_b32_e32 v220, 16, v196
	v_and_b32_e32 v221, 0xffff0000, v196
	v_pk_mul_f32 v[220:221], v[158:159], v[220:221] op_sel_hi:[0,1]
	v_pk_mul_f32 v[220:221], v[222:223], v[220:221]
	v_pk_mul_f32 v[222:223], v[96:97], s[64:65] op_sel_hi:[1,0]
	v_cvt_pk_bf16_f32 v196, v220, v221
	v_exp_f32_e32 v222, v222
	v_exp_f32_e32 v223, v223
	v_lshlrev_b32_e32 v220, 16, v197
	v_and_b32_e32 v221, 0xffff0000, v197
	v_pk_mul_f32 v[220:221], v[158:159], v[220:221] op_sel_hi:[0,1]
	v_pk_add_f32 v[222:223], v[222:223], 1.0 op_sel_hi:[1,0]
	s_nop 0
	v_rcp_f32_e32 v222, v222
	v_rcp_f32_e32 v223, v223
	s_nop 0
	v_pk_mul_f32 v[222:223], v[222:223], v[144:145]
	s_nop 0
	v_pk_mul_f32 v[220:221], v[222:223], v[220:221]
	v_pk_mul_f32 v[222:223], v[90:91], s[64:65] op_sel_hi:[1,0]
	v_cvt_pk_bf16_f32 v197, v220, v221
	v_exp_f32_e32 v222, v222
	v_exp_f32_e32 v223, v223
	v_lshlrev_b32_e32 v220, 16, v198
	v_and_b32_e32 v221, 0xffff0000, v198
	v_pk_mul_f32 v[220:221], v[158:159], v[220:221] op_sel_hi:[0,1]
	v_pk_add_f32 v[222:223], v[222:223], 1.0 op_sel_hi:[1,0]
	s_nop 0
	v_rcp_f32_e32 v222, v222
	v_rcp_f32_e32 v223, v223
	s_nop 0
	v_pk_mul_f32 v[222:223], v[222:223], v[138:139]
	s_nop 0
	v_pk_mul_f32 v[220:221], v[222:223], v[220:221]
	v_pk_mul_f32 v[222:223], v[92:93], s[64:65] op_sel_hi:[1,0]
	v_cvt_pk_bf16_f32 v198, v220, v221
	v_exp_f32_e32 v222, v222
	v_exp_f32_e32 v223, v223
	v_lshlrev_b32_e32 v220, 16, v199
	v_and_b32_e32 v221, 0xffff0000, v199
	v_pk_mul_f32 v[220:221], v[158:159], v[220:221] op_sel_hi:[0,1]
	v_pk_add_f32 v[222:223], v[222:223], 1.0 op_sel_hi:[1,0]
	s_nop 0
	v_rcp_f32_e32 v222, v222
	v_rcp_f32_e32 v223, v223
	s_nop 0
	v_pk_mul_f32 v[222:223], v[222:223], v[140:141]
	s_nop 0
	v_pk_mul_f32 v[220:221], v[222:223], v[220:221]
	v_pk_mul_f32 v[222:223], v[62:63], s[64:65] op_sel_hi:[1,0]
	v_cvt_pk_bf16_f32 v199, v220, v221
	global_store_dwordx4 v[218:219], v[196:199], off
	v_exp_f32_e32 v222, v222
	v_exp_f32_e32 v223, v223
	v_pk_mul_f32 v[198:199], v[86:87], s[64:65] op_sel_hi:[1,0]
	s_waitcnt vmcnt(3)
	v_lshlrev_b32_e32 v196, 16, v170
	v_exp_f32_e32 v198, v198
	v_exp_f32_e32 v199, v199
	v_and_b32_e32 v197, 0xffff0000, v170
	v_pk_mul_f32 v[196:197], v[158:159], v[196:197] op_sel_hi:[0,1]
	v_pk_add_f32 v[222:223], v[222:223], 1.0 op_sel_hi:[1,0]
	v_pk_add_f32 v[198:199], v[198:199], 1.0 op_sel_hi:[1,0]
	v_rcp_f32_e32 v222, v222
	v_rcp_f32_e32 v198, v198
	v_rcp_f32_e32 v199, v199
	v_rcp_f32_e32 v223, v223
	v_pk_mul_f32 v[198:199], v[198:199], v[134:135]
	s_nop 0
	v_pk_mul_f32 v[196:197], v[198:199], v[196:197]
	v_pk_mul_f32 v[198:199], v[88:89], s[64:65] op_sel_hi:[1,0]
	v_cvt_pk_bf16_f32 v170, v196, v197
	v_exp_f32_e32 v198, v198
	v_exp_f32_e32 v199, v199
	v_lshlrev_b32_e32 v196, 16, v171
	v_and_b32_e32 v197, 0xffff0000, v171
	v_pk_mul_f32 v[196:197], v[158:159], v[196:197] op_sel_hi:[0,1]
	v_pk_add_f32 v[198:199], v[198:199], 1.0 op_sel_hi:[1,0]
	v_pk_mul_f32 v[222:223], v[222:223], v[142:143]
	v_rcp_f32_e32 v198, v198
	v_rcp_f32_e32 v199, v199
	s_nop 0
	v_pk_mul_f32 v[198:199], v[198:199], v[136:137]
	s_nop 0
	v_pk_mul_f32 v[196:197], v[198:199], v[196:197]
	v_pk_mul_f32 v[198:199], v[82:83], s[64:65] op_sel_hi:[1,0]
	v_cvt_pk_bf16_f32 v171, v196, v197
	v_exp_f32_e32 v198, v198
	v_exp_f32_e32 v199, v199
	v_lshlrev_b32_e32 v196, 16, v172
	v_and_b32_e32 v197, 0xffff0000, v172
	v_pk_mul_f32 v[196:197], v[158:159], v[196:197] op_sel_hi:[0,1]
	v_pk_add_f32 v[198:199], v[198:199], 1.0 op_sel_hi:[1,0]
	s_nop 0
	v_rcp_f32_e32 v198, v198
	v_rcp_f32_e32 v199, v199
	s_nop 0
	v_pk_mul_f32 v[198:199], v[198:199], v[130:131]
	s_nop 0
	v_pk_mul_f32 v[196:197], v[198:199], v[196:197]
	v_pk_mul_f32 v[198:199], v[84:85], s[64:65] op_sel_hi:[1,0]
	v_cvt_pk_bf16_f32 v172, v196, v197
	v_exp_f32_e32 v198, v198
	v_exp_f32_e32 v199, v199
	v_lshlrev_b32_e32 v196, 16, v173
	v_and_b32_e32 v197, 0xffff0000, v173
	v_pk_mul_f32 v[196:197], v[158:159], v[196:197] op_sel_hi:[0,1]
	v_pk_add_f32 v[198:199], v[198:199], 1.0 op_sel_hi:[1,0]
	s_waitcnt vmcnt(3)
	v_fmamk_f32 v158, v239, 0x3b800000, v229
	v_rcp_f32_e32 v198, v198
	v_rcp_f32_e32 v199, v199
	v_rsq_f32_e32 v158, v158
	v_pk_mul_f32 v[198:199], v[198:199], v[132:133]
	s_nop 0
	v_pk_mul_f32 v[196:197], v[198:199], v[196:197]
	s_nop 0
	v_cvt_pk_bf16_f32 v173, v196, v197
	global_store_dwordx4 v[218:219], v[170:173], off offset:256
	s_nop 1
	v_pk_mul_f32 v[172:173], v[78:79], s[64:65] op_sel_hi:[1,0]
	s_waitcnt vmcnt(3)
	v_lshlrev_b32_e32 v170, 16, v166
	v_exp_f32_e32 v172, v172
	v_exp_f32_e32 v173, v173
	v_and_b32_e32 v171, 0xffff0000, v166
	v_pk_mul_f32 v[170:171], v[158:159], v[170:171] op_sel_hi:[0,1]
	v_pk_add_f32 v[172:173], v[172:173], 1.0 op_sel_hi:[1,0]
	s_nop 0
	v_rcp_f32_e32 v172, v172
	v_rcp_f32_e32 v173, v173
	s_nop 0
	v_pk_mul_f32 v[172:173], v[172:173], v[142:143]
	s_nop 0
	v_pk_mul_f32 v[170:171], v[172:173], v[170:171]
	v_pk_mul_f32 v[172:173], v[80:81], s[64:65] op_sel_hi:[1,0]
	v_cvt_pk_bf16_f32 v166, v170, v171
	v_exp_f32_e32 v172, v172
	v_exp_f32_e32 v173, v173
	v_lshlrev_b32_e32 v170, 16, v167
	v_and_b32_e32 v171, 0xffff0000, v167
	v_pk_mul_f32 v[170:171], v[158:159], v[170:171] op_sel_hi:[0,1]
	v_pk_add_f32 v[172:173], v[172:173], 1.0 op_sel_hi:[1,0]
	s_nop 0
	v_rcp_f32_e32 v172, v172
	v_rcp_f32_e32 v173, v173
	s_nop 0
	v_pk_mul_f32 v[172:173], v[172:173], v[144:145]
	s_nop 0
	v_pk_mul_f32 v[170:171], v[172:173], v[170:171]
	v_pk_mul_f32 v[172:173], v[74:75], s[64:65] op_sel_hi:[1,0]
	v_cvt_pk_bf16_f32 v167, v170, v171
	v_exp_f32_e32 v172, v172
	v_exp_f32_e32 v173, v173
	v_lshlrev_b32_e32 v170, 16, v168
	v_and_b32_e32 v171, 0xffff0000, v168
	v_pk_mul_f32 v[170:171], v[158:159], v[170:171] op_sel_hi:[0,1]
	v_pk_add_f32 v[172:173], v[172:173], 1.0 op_sel_hi:[1,0]
	s_nop 0
	v_rcp_f32_e32 v172, v172
	v_rcp_f32_e32 v173, v173
	s_nop 0
	v_pk_mul_f32 v[172:173], v[172:173], v[138:139]
	s_nop 0
	v_pk_mul_f32 v[170:171], v[172:173], v[170:171]
	v_pk_mul_f32 v[172:173], v[76:77], s[64:65] op_sel_hi:[1,0]
	v_cvt_pk_bf16_f32 v168, v170, v171
	v_exp_f32_e32 v172, v172
	v_exp_f32_e32 v173, v173
	v_lshlrev_b32_e32 v170, 16, v169
	v_and_b32_e32 v171, 0xffff0000, v169
	v_pk_mul_f32 v[170:171], v[158:159], v[170:171] op_sel_hi:[0,1]
	v_pk_add_f32 v[172:173], v[172:173], 1.0 op_sel_hi:[1,0]
	s_nop 0
	v_rcp_f32_e32 v172, v172
	v_rcp_f32_e32 v173, v173
	s_nop 0
	v_pk_mul_f32 v[172:173], v[172:173], v[140:141]
	s_nop 0
	v_pk_mul_f32 v[170:171], v[172:173], v[170:171]
	s_nop 0
	v_cvt_pk_bf16_f32 v169, v170, v171
	v_lshl_add_u64 v[170:171], s[20:21], 0, v[212:213]
	v_lshl_add_u64 v[170:171], v[170:171], 0, v[190:191]
	global_store_dwordx4 v[170:171], v[166:169], off
	s_nop 1
	v_pk_mul_f32 v[168:169], v[70:71], s[64:65] op_sel_hi:[1,0]
	s_waitcnt vmcnt(3)
	v_lshlrev_b32_e32 v166, 16, v162
	v_exp_f32_e32 v168, v168
	v_exp_f32_e32 v169, v169
	v_and_b32_e32 v167, 0xffff0000, v162
	v_pk_mul_f32 v[166:167], v[158:159], v[166:167] op_sel_hi:[0,1]
	v_pk_add_f32 v[168:169], v[168:169], 1.0 op_sel_hi:[1,0]
	s_nop 0
	v_rcp_f32_e32 v168, v168
	v_rcp_f32_e32 v169, v169
	s_nop 0
	v_pk_mul_f32 v[168:169], v[168:169], v[134:135]
	s_nop 0
	v_pk_mul_f32 v[166:167], v[168:169], v[166:167]
	v_pk_mul_f32 v[168:169], v[72:73], s[64:65] op_sel_hi:[1,0]
	v_cvt_pk_bf16_f32 v162, v166, v167
	v_exp_f32_e32 v168, v168
	v_exp_f32_e32 v169, v169
	v_lshlrev_b32_e32 v166, 16, v163
	v_and_b32_e32 v167, 0xffff0000, v163
	v_pk_mul_f32 v[166:167], v[158:159], v[166:167] op_sel_hi:[0,1]
	v_pk_add_f32 v[168:169], v[168:169], 1.0 op_sel_hi:[1,0]
	s_nop 0
	v_rcp_f32_e32 v168, v168
	v_rcp_f32_e32 v169, v169
	s_nop 0
	v_pk_mul_f32 v[168:169], v[168:169], v[136:137]
	s_nop 0
	v_pk_mul_f32 v[166:167], v[168:169], v[166:167]
	v_pk_mul_f32 v[168:169], v[66:67], s[64:65] op_sel_hi:[1,0]
	v_cvt_pk_bf16_f32 v163, v166, v167
	v_exp_f32_e32 v168, v168
	v_exp_f32_e32 v169, v169
	v_lshlrev_b32_e32 v166, 16, v164
	v_and_b32_e32 v167, 0xffff0000, v164
	v_pk_mul_f32 v[166:167], v[158:159], v[166:167] op_sel_hi:[0,1]
	v_pk_add_f32 v[168:169], v[168:169], 1.0 op_sel_hi:[1,0]
	s_nop 0
	v_rcp_f32_e32 v168, v168
	v_rcp_f32_e32 v169, v169
	s_nop 0
	v_pk_mul_f32 v[168:169], v[168:169], v[130:131]
	s_nop 0
	v_pk_mul_f32 v[166:167], v[168:169], v[166:167]
	v_pk_mul_f32 v[168:169], v[68:69], s[64:65] op_sel_hi:[1,0]
	v_cvt_pk_bf16_f32 v164, v166, v167
	v_exp_f32_e32 v168, v168
	v_exp_f32_e32 v169, v169
	v_lshlrev_b32_e32 v166, 16, v165
	v_and_b32_e32 v167, 0xffff0000, v165
	v_pk_mul_f32 v[166:167], v[158:159], v[166:167] op_sel_hi:[0,1]
	v_pk_add_f32 v[168:169], v[168:169], 1.0 op_sel_hi:[1,0]
	s_nop 0
	v_rcp_f32_e32 v168, v168
	v_rcp_f32_e32 v169, v169
	s_nop 0
	v_pk_mul_f32 v[168:169], v[168:169], v[132:133]
	s_nop 0
	v_pk_mul_f32 v[166:167], v[168:169], v[166:167]
	s_nop 0
	v_cvt_pk_bf16_f32 v165, v166, v167
	global_store_dwordx4 v[170:171], v[162:165], off offset:256
	s_waitcnt vmcnt(4)
	v_fmamk_f32 v158, v240, 0x3b800000, v229
	v_add_u32_e32 v162, 0x80, v186
	v_ashrrev_i32_e32 v163, 31, v162
	v_lshlrev_b64 v[218:219], 12, v[162:163]
	v_lshl_add_u64 v[162:163], v[200:201], 0, v[218:219]
	global_load_dwordx4 v[196:199], v[162:163], off
	global_load_dwordx4 v[170:173], v[162:163], off offset:256
	v_rsq_f32_e32 v158, v158
	v_add_u32_e32 v162, 0x90, v186
	v_ashrrev_i32_e32 v163, 31, v162
	v_lshlrev_b64 v[212:213], 12, v[162:163]
	v_lshl_add_u64 v[162:163], v[200:201], 0, v[212:213]
	global_load_dwordx4 v[166:169], v[162:163], off
	s_nop 0
	global_load_dwordx4 v[162:165], v[162:163], off offset:256
	v_lshl_add_u64 v[218:219], s[20:21], 0, v[218:219]
	v_lshl_add_u64 v[218:219], v[218:219], 0, v[190:191]
	s_waitcnt vmcnt(3)
	v_lshlrev_b32_e32 v220, 16, v196
	v_and_b32_e32 v221, 0xffff0000, v196
	v_pk_mul_f32 v[220:221], v[158:159], v[220:221] op_sel_hi:[0,1]
	v_pk_mul_f32 v[220:221], v[222:223], v[220:221]
	v_pk_mul_f32 v[222:223], v[64:65], s[64:65] op_sel_hi:[1,0]
	v_cvt_pk_bf16_f32 v196, v220, v221
	v_exp_f32_e32 v222, v222
	v_exp_f32_e32 v223, v223
	v_lshlrev_b32_e32 v220, 16, v197
	v_and_b32_e32 v221, 0xffff0000, v197
	v_pk_mul_f32 v[220:221], v[158:159], v[220:221] op_sel_hi:[0,1]
	v_pk_add_f32 v[222:223], v[222:223], 1.0 op_sel_hi:[1,0]
	s_nop 0
	v_rcp_f32_e32 v222, v222
	v_rcp_f32_e32 v223, v223
	s_nop 0
	v_pk_mul_f32 v[222:223], v[222:223], v[144:145]
	s_nop 0
	v_pk_mul_f32 v[220:221], v[222:223], v[220:221]
	v_pk_mul_f32 v[222:223], v[58:59], s[64:65] op_sel_hi:[1,0]
	v_cvt_pk_bf16_f32 v197, v220, v221
	v_exp_f32_e32 v222, v222
	v_exp_f32_e32 v223, v223
	v_lshlrev_b32_e32 v220, 16, v198
	v_and_b32_e32 v221, 0xffff0000, v198
	v_pk_mul_f32 v[220:221], v[158:159], v[220:221] op_sel_hi:[0,1]
	v_pk_add_f32 v[222:223], v[222:223], 1.0 op_sel_hi:[1,0]
	s_nop 0
	v_rcp_f32_e32 v222, v222
	v_rcp_f32_e32 v223, v223
	s_nop 0
	v_pk_mul_f32 v[222:223], v[222:223], v[138:139]
	s_nop 0
	v_pk_mul_f32 v[220:221], v[222:223], v[220:221]
	v_pk_mul_f32 v[222:223], v[60:61], s[64:65] op_sel_hi:[1,0]
	v_cvt_pk_bf16_f32 v198, v220, v221
	v_exp_f32_e32 v222, v222
	v_exp_f32_e32 v223, v223
	v_lshlrev_b32_e32 v220, 16, v199
	v_and_b32_e32 v221, 0xffff0000, v199
	v_pk_mul_f32 v[220:221], v[158:159], v[220:221] op_sel_hi:[0,1]
	v_pk_add_f32 v[222:223], v[222:223], 1.0 op_sel_hi:[1,0]
	s_nop 0
	v_rcp_f32_e32 v222, v222
	v_rcp_f32_e32 v223, v223
	s_nop 0
	v_pk_mul_f32 v[222:223], v[222:223], v[140:141]
	s_nop 0
	v_pk_mul_f32 v[220:221], v[222:223], v[220:221]
	s_nop 0
	v_cvt_pk_bf16_f32 v199, v220, v221
	global_store_dwordx4 v[218:219], v[196:199], off
	v_pk_mul_f32 v[220:221], v[30:31], s[64:65] op_sel_hi:[1,0]
	s_nop 0
	v_pk_mul_f32 v[198:199], v[54:55], s[64:65] op_sel_hi:[1,0]
	s_waitcnt vmcnt(3)
	v_lshlrev_b32_e32 v196, 16, v170
	v_exp_f32_e32 v198, v198
	v_exp_f32_e32 v199, v199
	v_and_b32_e32 v197, 0xffff0000, v170
	v_pk_mul_f32 v[196:197], v[158:159], v[196:197] op_sel_hi:[0,1]
	v_exp_f32_e32 v220, v220
	v_pk_add_f32 v[198:199], v[198:199], 1.0 op_sel_hi:[1,0]
	v_exp_f32_e32 v221, v221
	v_rcp_f32_e32 v198, v198
	v_rcp_f32_e32 v199, v199
	v_pk_add_f32 v[220:221], v[220:221], 1.0 op_sel_hi:[1,0]
	s_nop 0
	v_rcp_f32_e32 v220, v220
	v_pk_mul_f32 v[198:199], v[198:199], v[134:135]
	v_rcp_f32_e32 v221, v221
	v_pk_mul_f32 v[196:197], v[198:199], v[196:197]
	v_pk_mul_f32 v[198:199], v[56:57], s[64:65] op_sel_hi:[1,0]
	v_cvt_pk_bf16_f32 v170, v196, v197
	v_exp_f32_e32 v198, v198
	v_exp_f32_e32 v199, v199
	v_lshlrev_b32_e32 v196, 16, v171
	v_and_b32_e32 v197, 0xffff0000, v171
	v_pk_mul_f32 v[196:197], v[158:159], v[196:197] op_sel_hi:[0,1]
	v_pk_add_f32 v[198:199], v[198:199], 1.0 op_sel_hi:[1,0]
	v_pk_mul_f32 v[220:221], v[220:221], v[142:143]
	v_rcp_f32_e32 v198, v198
	v_rcp_f32_e32 v199, v199
	s_nop 0
	v_pk_mul_f32 v[198:199], v[198:199], v[136:137]
	s_nop 0
	v_pk_mul_f32 v[196:197], v[198:199], v[196:197]
	v_pk_mul_f32 v[198:199], v[50:51], s[64:65] op_sel_hi:[1,0]
	v_cvt_pk_bf16_f32 v171, v196, v197
	v_exp_f32_e32 v198, v198
	v_exp_f32_e32 v199, v199
	v_lshlrev_b32_e32 v196, 16, v172
	v_and_b32_e32 v197, 0xffff0000, v172
	v_pk_mul_f32 v[196:197], v[158:159], v[196:197] op_sel_hi:[0,1]
	v_pk_add_f32 v[198:199], v[198:199], 1.0 op_sel_hi:[1,0]
	s_nop 0
	v_rcp_f32_e32 v198, v198
	v_rcp_f32_e32 v199, v199
	s_nop 0
	v_pk_mul_f32 v[198:199], v[198:199], v[130:131]
	s_nop 0
	v_pk_mul_f32 v[196:197], v[198:199], v[196:197]
	v_pk_mul_f32 v[198:199], v[52:53], s[64:65] op_sel_hi:[1,0]
	v_cvt_pk_bf16_f32 v172, v196, v197
	v_exp_f32_e32 v198, v198
	v_exp_f32_e32 v199, v199
	v_lshlrev_b32_e32 v196, 16, v173
	v_and_b32_e32 v197, 0xffff0000, v173
	v_pk_mul_f32 v[196:197], v[158:159], v[196:197] op_sel_hi:[0,1]
	v_pk_add_f32 v[198:199], v[198:199], 1.0 op_sel_hi:[1,0]
	s_waitcnt vmcnt(3)
	v_fmamk_f32 v158, v241, 0x3b800000, v229
	v_rcp_f32_e32 v198, v198
	v_rcp_f32_e32 v199, v199
	v_rsq_f32_e32 v158, v158
	v_pk_mul_f32 v[198:199], v[198:199], v[132:133]
	s_nop 0
	v_pk_mul_f32 v[196:197], v[198:199], v[196:197]
	s_nop 0
	v_cvt_pk_bf16_f32 v173, v196, v197
	global_store_dwordx4 v[218:219], v[170:173], off offset:256
	s_nop 1
	v_pk_mul_f32 v[172:173], v[46:47], s[64:65] op_sel_hi:[1,0]
	s_waitcnt vmcnt(3)
	v_lshlrev_b32_e32 v170, 16, v166
	v_exp_f32_e32 v172, v172
	v_exp_f32_e32 v173, v173
	v_and_b32_e32 v171, 0xffff0000, v166
	v_pk_mul_f32 v[170:171], v[158:159], v[170:171] op_sel_hi:[0,1]
	v_pk_add_f32 v[172:173], v[172:173], 1.0 op_sel_hi:[1,0]
	s_nop 0
	v_rcp_f32_e32 v172, v172
	v_rcp_f32_e32 v173, v173
	s_nop 0
	v_pk_mul_f32 v[172:173], v[172:173], v[142:143]
	s_nop 0
	v_pk_mul_f32 v[170:171], v[172:173], v[170:171]
	v_pk_mul_f32 v[172:173], v[48:49], s[64:65] op_sel_hi:[1,0]
	v_cvt_pk_bf16_f32 v166, v170, v171
	v_exp_f32_e32 v172, v172
	v_exp_f32_e32 v173, v173
	v_lshlrev_b32_e32 v170, 16, v167
	v_and_b32_e32 v171, 0xffff0000, v167
	v_pk_mul_f32 v[170:171], v[158:159], v[170:171] op_sel_hi:[0,1]
	v_pk_add_f32 v[172:173], v[172:173], 1.0 op_sel_hi:[1,0]
	s_nop 0
	v_rcp_f32_e32 v172, v172
	v_rcp_f32_e32 v173, v173
	s_nop 0
	v_pk_mul_f32 v[172:173], v[172:173], v[144:145]
	s_nop 0
	v_pk_mul_f32 v[170:171], v[172:173], v[170:171]
	v_pk_mul_f32 v[172:173], v[42:43], s[64:65] op_sel_hi:[1,0]
	v_cvt_pk_bf16_f32 v167, v170, v171
	v_exp_f32_e32 v172, v172
	v_exp_f32_e32 v173, v173
	v_lshlrev_b32_e32 v170, 16, v168
	v_and_b32_e32 v171, 0xffff0000, v168
	v_pk_mul_f32 v[170:171], v[158:159], v[170:171] op_sel_hi:[0,1]
	v_pk_add_f32 v[172:173], v[172:173], 1.0 op_sel_hi:[1,0]
	s_nop 0
	v_rcp_f32_e32 v172, v172
	v_rcp_f32_e32 v173, v173
	s_nop 0
	v_pk_mul_f32 v[172:173], v[172:173], v[138:139]
	s_nop 0
	v_pk_mul_f32 v[170:171], v[172:173], v[170:171]
	v_pk_mul_f32 v[172:173], v[44:45], s[64:65] op_sel_hi:[1,0]
	v_cvt_pk_bf16_f32 v168, v170, v171
	v_exp_f32_e32 v172, v172
	v_exp_f32_e32 v173, v173
	v_lshlrev_b32_e32 v170, 16, v169
	v_and_b32_e32 v171, 0xffff0000, v169
	v_pk_mul_f32 v[170:171], v[158:159], v[170:171] op_sel_hi:[0,1]
	v_pk_add_f32 v[172:173], v[172:173], 1.0 op_sel_hi:[1,0]
	s_nop 0
	v_rcp_f32_e32 v172, v172
	v_rcp_f32_e32 v173, v173
	s_nop 0
	v_pk_mul_f32 v[172:173], v[172:173], v[140:141]
	s_nop 0
	v_pk_mul_f32 v[170:171], v[172:173], v[170:171]
	s_nop 0
	v_cvt_pk_bf16_f32 v169, v170, v171
	v_lshl_add_u64 v[170:171], s[20:21], 0, v[212:213]
	v_lshl_add_u64 v[170:171], v[170:171], 0, v[190:191]
	global_store_dwordx4 v[170:171], v[166:169], off
	s_nop 1
	v_pk_mul_f32 v[168:169], v[38:39], s[64:65] op_sel_hi:[1,0]
	s_waitcnt vmcnt(3)
	v_lshlrev_b32_e32 v166, 16, v162
	v_exp_f32_e32 v168, v168
	v_exp_f32_e32 v169, v169
	v_and_b32_e32 v167, 0xffff0000, v162
	v_pk_mul_f32 v[166:167], v[158:159], v[166:167] op_sel_hi:[0,1]
	v_pk_add_f32 v[168:169], v[168:169], 1.0 op_sel_hi:[1,0]
	s_nop 0
	v_rcp_f32_e32 v168, v168
	v_rcp_f32_e32 v169, v169
	s_nop 0
	v_pk_mul_f32 v[168:169], v[168:169], v[134:135]
	s_nop 0
	v_pk_mul_f32 v[166:167], v[168:169], v[166:167]
	v_pk_mul_f32 v[168:169], v[40:41], s[64:65] op_sel_hi:[1,0]
	v_cvt_pk_bf16_f32 v162, v166, v167
	v_exp_f32_e32 v168, v168
	v_exp_f32_e32 v169, v169
	v_lshlrev_b32_e32 v166, 16, v163
	v_and_b32_e32 v167, 0xffff0000, v163
	v_pk_mul_f32 v[166:167], v[158:159], v[166:167] op_sel_hi:[0,1]
	v_pk_add_f32 v[168:169], v[168:169], 1.0 op_sel_hi:[1,0]
	s_nop 0
	v_rcp_f32_e32 v168, v168
	v_rcp_f32_e32 v169, v169
	s_nop 0
	v_pk_mul_f32 v[168:169], v[168:169], v[136:137]
	s_nop 0
	v_pk_mul_f32 v[166:167], v[168:169], v[166:167]
	v_pk_mul_f32 v[168:169], v[34:35], s[64:65] op_sel_hi:[1,0]
	v_cvt_pk_bf16_f32 v163, v166, v167
	v_exp_f32_e32 v168, v168
	v_exp_f32_e32 v169, v169
	v_lshlrev_b32_e32 v166, 16, v164
	v_and_b32_e32 v167, 0xffff0000, v164
	v_pk_mul_f32 v[166:167], v[158:159], v[166:167] op_sel_hi:[0,1]
	v_pk_add_f32 v[168:169], v[168:169], 1.0 op_sel_hi:[1,0]
	s_nop 0
	v_rcp_f32_e32 v168, v168
	v_rcp_f32_e32 v169, v169
	s_nop 0
	v_pk_mul_f32 v[168:169], v[168:169], v[130:131]
	s_nop 0
	v_pk_mul_f32 v[166:167], v[168:169], v[166:167]
	v_pk_mul_f32 v[168:169], v[36:37], s[64:65] op_sel_hi:[1,0]
	v_cvt_pk_bf16_f32 v164, v166, v167
	v_exp_f32_e32 v168, v168
	v_exp_f32_e32 v169, v169
	v_lshlrev_b32_e32 v166, 16, v165
	v_and_b32_e32 v167, 0xffff0000, v165
	v_pk_mul_f32 v[166:167], v[158:159], v[166:167] op_sel_hi:[0,1]
	v_pk_add_f32 v[168:169], v[168:169], 1.0 op_sel_hi:[1,0]
	s_nop 0
	v_rcp_f32_e32 v168, v168
	v_rcp_f32_e32 v169, v169
	s_nop 0
	v_pk_mul_f32 v[168:169], v[168:169], v[132:133]
	s_nop 0
	v_pk_mul_f32 v[166:167], v[168:169], v[166:167]
	s_nop 0
	v_cvt_pk_bf16_f32 v165, v166, v167
	global_store_dwordx4 v[170:171], v[162:165], off offset:256
	s_waitcnt vmcnt(4)
	v_fmamk_f32 v158, v242, 0x3b800000, v229
	v_add_u32_e32 v162, 0xa0, v186
	v_ashrrev_i32_e32 v163, 31, v162
	v_lshlrev_b64 v[212:213], 12, v[162:163]
	v_lshl_add_u64 v[162:163], v[200:201], 0, v[212:213]
	global_load_dwordx4 v[196:199], v[162:163], off
	global_load_dwordx4 v[170:173], v[162:163], off offset:256
	v_rsq_f32_e32 v158, v158
	v_add_u32_e32 v162, 0xb0, v186
	v_ashrrev_i32_e32 v163, 31, v162
	v_lshlrev_b64 v[210:211], 12, v[162:163]
	v_lshl_add_u64 v[162:163], v[200:201], 0, v[210:211]
	global_load_dwordx4 v[166:169], v[162:163], off
	s_nop 0
	global_load_dwordx4 v[162:165], v[162:163], off offset:256
	v_lshl_add_u64 v[212:213], s[20:21], 0, v[212:213]
	v_lshl_add_u64 v[212:213], v[212:213], 0, v[190:191]
	s_waitcnt vmcnt(3)
	v_lshlrev_b32_e32 v218, 16, v196
	v_and_b32_e32 v219, 0xffff0000, v196
	v_pk_mul_f32 v[218:219], v[158:159], v[218:219] op_sel_hi:[0,1]
	v_pk_mul_f32 v[218:219], v[220:221], v[218:219]
	v_pk_mul_f32 v[220:221], v[32:33], s[64:65] op_sel_hi:[1,0]
	v_cvt_pk_bf16_f32 v196, v218, v219
	v_exp_f32_e32 v220, v220
	v_exp_f32_e32 v221, v221
	v_lshlrev_b32_e32 v218, 16, v197
	v_and_b32_e32 v219, 0xffff0000, v197
	v_pk_mul_f32 v[218:219], v[158:159], v[218:219] op_sel_hi:[0,1]
	v_pk_add_f32 v[220:221], v[220:221], 1.0 op_sel_hi:[1,0]
	s_nop 0
	v_rcp_f32_e32 v220, v220
	v_rcp_f32_e32 v221, v221
	s_nop 0
	v_pk_mul_f32 v[220:221], v[220:221], v[144:145]
	s_nop 0
	v_pk_mul_f32 v[218:219], v[220:221], v[218:219]
	v_pk_mul_f32 v[220:221], v[26:27], s[64:65] op_sel_hi:[1,0]
	v_cvt_pk_bf16_f32 v197, v218, v219
	v_exp_f32_e32 v220, v220
	v_exp_f32_e32 v221, v221
	v_lshlrev_b32_e32 v218, 16, v198
	v_and_b32_e32 v219, 0xffff0000, v198
	v_pk_mul_f32 v[218:219], v[158:159], v[218:219] op_sel_hi:[0,1]
	v_pk_add_f32 v[220:221], v[220:221], 1.0 op_sel_hi:[1,0]
	s_nop 0
	v_rcp_f32_e32 v220, v220
	v_rcp_f32_e32 v221, v221
	s_nop 0
	v_pk_mul_f32 v[220:221], v[220:221], v[138:139]
	s_nop 0
	v_pk_mul_f32 v[218:219], v[220:221], v[218:219]
	v_pk_mul_f32 v[220:221], v[28:29], s[64:65] op_sel_hi:[1,0]
	v_cvt_pk_bf16_f32 v198, v218, v219
	v_exp_f32_e32 v220, v220
	v_exp_f32_e32 v221, v221
	v_lshlrev_b32_e32 v218, 16, v199
	v_and_b32_e32 v219, 0xffff0000, v199
	v_pk_mul_f32 v[218:219], v[158:159], v[218:219] op_sel_hi:[0,1]
	v_pk_add_f32 v[220:221], v[220:221], 1.0 op_sel_hi:[1,0]
	s_nop 0
	v_rcp_f32_e32 v220, v220
	v_rcp_f32_e32 v221, v221
	s_nop 0
	v_pk_mul_f32 v[220:221], v[220:221], v[140:141]
	s_nop 0
	v_pk_mul_f32 v[218:219], v[220:221], v[218:219]
	s_nop 0
	v_cvt_pk_bf16_f32 v199, v218, v219
	global_store_dwordx4 v[212:213], v[196:199], off
	s_nop 1
	v_pk_mul_f32 v[198:199], v[22:23], s[64:65] op_sel_hi:[1,0]
	s_waitcnt vmcnt(3)
	v_lshlrev_b32_e32 v196, 16, v170
	v_exp_f32_e32 v198, v198
	v_exp_f32_e32 v199, v199
	v_and_b32_e32 v197, 0xffff0000, v170
	v_pk_mul_f32 v[196:197], v[158:159], v[196:197] op_sel_hi:[0,1]
	v_pk_add_f32 v[198:199], v[198:199], 1.0 op_sel_hi:[1,0]
	s_nop 0
	v_rcp_f32_e32 v198, v198
	v_rcp_f32_e32 v199, v199
	s_nop 0
	v_pk_mul_f32 v[198:199], v[198:199], v[134:135]
	s_nop 0
	v_pk_mul_f32 v[196:197], v[198:199], v[196:197]
	v_pk_mul_f32 v[198:199], v[24:25], s[64:65] op_sel_hi:[1,0]
	v_cvt_pk_bf16_f32 v170, v196, v197
	v_exp_f32_e32 v198, v198
	v_exp_f32_e32 v199, v199
	v_lshlrev_b32_e32 v196, 16, v171
	v_and_b32_e32 v197, 0xffff0000, v171
	v_pk_mul_f32 v[196:197], v[158:159], v[196:197] op_sel_hi:[0,1]
	v_pk_add_f32 v[198:199], v[198:199], 1.0 op_sel_hi:[1,0]
	s_nop 0
	v_rcp_f32_e32 v198, v198
	v_rcp_f32_e32 v199, v199
	s_nop 0
	v_pk_mul_f32 v[198:199], v[198:199], v[136:137]
	s_nop 0
	v_pk_mul_f32 v[196:197], v[198:199], v[196:197]
	v_pk_mul_f32 v[198:199], v[18:19], s[64:65] op_sel_hi:[1,0]
	v_cvt_pk_bf16_f32 v171, v196, v197
	v_exp_f32_e32 v198, v198
	v_exp_f32_e32 v199, v199
	v_lshlrev_b32_e32 v196, 16, v172
	v_and_b32_e32 v197, 0xffff0000, v172
	v_pk_mul_f32 v[196:197], v[158:159], v[196:197] op_sel_hi:[0,1]
	v_pk_add_f32 v[198:199], v[198:199], 1.0 op_sel_hi:[1,0]
	s_nop 0
	v_rcp_f32_e32 v198, v198
	v_rcp_f32_e32 v199, v199
	s_nop 0
	v_pk_mul_f32 v[198:199], v[198:199], v[130:131]
	s_nop 0
	v_pk_mul_f32 v[196:197], v[198:199], v[196:197]
	v_pk_mul_f32 v[198:199], v[20:21], s[64:65] op_sel_hi:[1,0]
	v_cvt_pk_bf16_f32 v172, v196, v197
	v_exp_f32_e32 v198, v198
	v_exp_f32_e32 v199, v199
	v_lshlrev_b32_e32 v196, 16, v173
	v_and_b32_e32 v197, 0xffff0000, v173
	v_pk_mul_f32 v[196:197], v[158:159], v[196:197] op_sel_hi:[0,1]
	v_pk_add_f32 v[198:199], v[198:199], 1.0 op_sel_hi:[1,0]
	s_waitcnt vmcnt(3)
	v_fmamk_f32 v158, v243, 0x3b800000, v229
	v_rcp_f32_e32 v198, v198
	v_rcp_f32_e32 v199, v199
	v_rsq_f32_e32 v158, v158
	v_pk_mul_f32 v[198:199], v[198:199], v[132:133]
	s_nop 0
	v_pk_mul_f32 v[196:197], v[198:199], v[196:197]
	s_nop 0
	v_cvt_pk_bf16_f32 v173, v196, v197
	global_store_dwordx4 v[212:213], v[170:173], off offset:256
	s_nop 1
	v_pk_mul_f32 v[172:173], v[14:15], s[64:65] op_sel_hi:[1,0]
	s_waitcnt vmcnt(3)
	v_lshlrev_b32_e32 v170, 16, v166
	v_exp_f32_e32 v172, v172
	v_exp_f32_e32 v173, v173
	v_and_b32_e32 v171, 0xffff0000, v166
	v_pk_mul_f32 v[170:171], v[158:159], v[170:171] op_sel_hi:[0,1]
	v_pk_add_f32 v[172:173], v[172:173], 1.0 op_sel_hi:[1,0]
	s_nop 0
	v_rcp_f32_e32 v172, v172
	v_rcp_f32_e32 v173, v173
	s_nop 0
	v_pk_mul_f32 v[172:173], v[172:173], v[142:143]
	s_nop 0
	v_pk_mul_f32 v[170:171], v[172:173], v[170:171]
	v_pk_mul_f32 v[172:173], v[16:17], s[64:65] op_sel_hi:[1,0]
	v_cvt_pk_bf16_f32 v166, v170, v171
	v_exp_f32_e32 v172, v172
	v_exp_f32_e32 v173, v173
	v_lshlrev_b32_e32 v170, 16, v167
	v_and_b32_e32 v171, 0xffff0000, v167
	v_pk_mul_f32 v[170:171], v[158:159], v[170:171] op_sel_hi:[0,1]
	v_pk_add_f32 v[172:173], v[172:173], 1.0 op_sel_hi:[1,0]
	s_nop 0
	v_rcp_f32_e32 v172, v172
	v_rcp_f32_e32 v173, v173
	s_nop 0
	v_pk_mul_f32 v[172:173], v[172:173], v[144:145]
	s_nop 0
	v_pk_mul_f32 v[170:171], v[172:173], v[170:171]
	v_pk_mul_f32 v[172:173], v[10:11], s[64:65] op_sel_hi:[1,0]
	v_cvt_pk_bf16_f32 v167, v170, v171
	v_exp_f32_e32 v172, v172
	v_exp_f32_e32 v173, v173
	v_lshlrev_b32_e32 v170, 16, v168
	v_and_b32_e32 v171, 0xffff0000, v168
	v_pk_mul_f32 v[170:171], v[158:159], v[170:171] op_sel_hi:[0,1]
	v_pk_add_f32 v[172:173], v[172:173], 1.0 op_sel_hi:[1,0]
	s_nop 0
	v_rcp_f32_e32 v172, v172
	v_rcp_f32_e32 v173, v173
	s_nop 0
	v_pk_mul_f32 v[172:173], v[172:173], v[138:139]
	s_nop 0
	v_pk_mul_f32 v[170:171], v[172:173], v[170:171]
	v_pk_mul_f32 v[172:173], v[12:13], s[64:65] op_sel_hi:[1,0]
	v_cvt_pk_bf16_f32 v168, v170, v171
	v_exp_f32_e32 v172, v172
	v_exp_f32_e32 v173, v173
	v_lshlrev_b32_e32 v170, 16, v169
	v_and_b32_e32 v171, 0xffff0000, v169
	v_pk_mul_f32 v[170:171], v[158:159], v[170:171] op_sel_hi:[0,1]
	v_pk_add_f32 v[172:173], v[172:173], 1.0 op_sel_hi:[1,0]
	s_nop 0
	v_rcp_f32_e32 v172, v172
	v_rcp_f32_e32 v173, v173
	s_nop 0
	v_pk_mul_f32 v[172:173], v[172:173], v[140:141]
	s_nop 0
	v_pk_mul_f32 v[170:171], v[172:173], v[170:171]
	s_nop 0
	v_cvt_pk_bf16_f32 v169, v170, v171
	v_lshl_add_u64 v[170:171], s[20:21], 0, v[210:211]
	v_lshl_add_u64 v[170:171], v[170:171], 0, v[190:191]
	global_store_dwordx4 v[170:171], v[166:169], off
	s_nop 1
	v_pk_mul_f32 v[168:169], v[6:7], s[64:65] op_sel_hi:[1,0]
	s_waitcnt vmcnt(3)
	v_lshlrev_b32_e32 v166, 16, v162
	v_exp_f32_e32 v168, v168
	v_exp_f32_e32 v169, v169
	v_and_b32_e32 v167, 0xffff0000, v162
	v_pk_mul_f32 v[166:167], v[158:159], v[166:167] op_sel_hi:[0,1]
	v_pk_add_f32 v[168:169], v[168:169], 1.0 op_sel_hi:[1,0]
	s_nop 0
	v_rcp_f32_e32 v168, v168
	v_rcp_f32_e32 v169, v169
	s_nop 0
	v_pk_mul_f32 v[168:169], v[168:169], v[134:135]
	s_nop 0
	v_pk_mul_f32 v[166:167], v[168:169], v[166:167]
	v_pk_mul_f32 v[168:169], v[8:9], s[64:65] op_sel_hi:[1,0]
	v_cvt_pk_bf16_f32 v162, v166, v167
	v_exp_f32_e32 v168, v168
	v_exp_f32_e32 v169, v169
	v_lshlrev_b32_e32 v166, 16, v163
	v_and_b32_e32 v167, 0xffff0000, v163
	v_pk_mul_f32 v[166:167], v[158:159], v[166:167] op_sel_hi:[0,1]
	v_pk_add_f32 v[168:169], v[168:169], 1.0 op_sel_hi:[1,0]
	s_nop 0
	v_rcp_f32_e32 v168, v168
	v_rcp_f32_e32 v169, v169
	s_nop 0
	v_pk_mul_f32 v[168:169], v[168:169], v[136:137]
	s_nop 0
	v_pk_mul_f32 v[166:167], v[168:169], v[166:167]
	v_pk_mul_f32 v[168:169], v[2:3], s[64:65] op_sel_hi:[1,0]
	v_cvt_pk_bf16_f32 v163, v166, v167
	v_exp_f32_e32 v168, v168
	v_exp_f32_e32 v169, v169
	v_lshlrev_b32_e32 v166, 16, v164
	v_and_b32_e32 v167, 0xffff0000, v164
	v_pk_mul_f32 v[166:167], v[158:159], v[166:167] op_sel_hi:[0,1]
	v_pk_add_f32 v[168:169], v[168:169], 1.0 op_sel_hi:[1,0]
	s_nop 0
	v_rcp_f32_e32 v168, v168
	v_rcp_f32_e32 v169, v169
	s_nop 0
	v_pk_mul_f32 v[168:169], v[168:169], v[130:131]
	s_nop 0
	v_pk_mul_f32 v[166:167], v[168:169], v[166:167]
	v_pk_mul_f32 v[168:169], v[4:5], s[64:65] op_sel_hi:[1,0]
	v_cvt_pk_bf16_f32 v164, v166, v167
	v_exp_f32_e32 v168, v168
	v_exp_f32_e32 v169, v169
	v_lshlrev_b32_e32 v166, 16, v165
	v_and_b32_e32 v167, 0xffff0000, v165
	v_pk_mul_f32 v[166:167], v[158:159], v[166:167] op_sel_hi:[0,1]
	v_pk_add_f32 v[168:169], v[168:169], 1.0 op_sel_hi:[1,0]
	s_nop 0
	v_rcp_f32_e32 v168, v168
	v_rcp_f32_e32 v169, v169
	s_nop 0
	v_pk_mul_f32 v[168:169], v[168:169], v[132:133]
	s_nop 0
	v_pk_mul_f32 v[166:167], v[168:169], v[166:167]
	s_nop 0
	v_cvt_pk_bf16_f32 v165, v166, v167
	global_store_dwordx4 v[170:171], v[162:165], off offset:256
.LBB0_680:
	s_andn2_b64 vcc, exec, s[22:23]
	s_cbranch_vccnz .LBB0_682
	s_mul_i32 s9, s9, 0x22000
	v_readlane_b32 s11, v254, 54
	s_add_u32 s18, s11, s9
	v_readlane_b32 s9, v254, 55
	s_addc_u32 s19, s9, 0
	v_lshl_add_u64 v[162:163], v[186:187], 2, s[18:19]
	global_load_dword v158, v[162:163], off
	global_load_dword v166, v[162:163], off offset:64
	global_load_dword v238, v[162:163], off offset:128
	global_load_dword v239, v[162:163], off offset:192
	global_load_dword v240, v[162:163], off offset:512
	global_load_dword v241, v[162:163], off offset:576
	global_load_dword v242, v[162:163], off offset:640
	global_load_dword v243, v[162:163], off offset:704
	v_pk_mul_f32 v[170:171], v[128:129], s[64:65] op_sel_hi:[1,0]
	v_pk_mul_f32 v[164:165], v[126:127], v[206:207]
	v_exp_f32_e32 v170, v170
	v_exp_f32_e32 v171, v171
	v_pk_mul_f32 v[164:165], v[164:165], v[142:143]
	v_pk_mul_f32 v[172:173], v[94:95], s[64:65] op_sel_hi:[1,0]
	v_pk_add_f32 v[170:171], v[170:171], 1.0 op_sel_hi:[1,0]
	s_nop 0
	v_rcp_f32_e32 v170, v170
	v_rcp_f32_e32 v171, v171
	v_exp_f32_e32 v172, v172
	v_exp_f32_e32 v173, v173
	v_pk_mul_f32 v[170:171], v[128:129], v[170:171]
	s_nop 0
	v_pk_mul_f32 v[170:171], v[170:171], v[144:145]
	v_pk_add_f32 v[172:173], v[172:173], 1.0 op_sel_hi:[1,0]
	s_waitcnt vmcnt(7)
	v_fmamk_f32 v158, v158, 0x3b800000, v229
	v_rsq_f32_e32 v158, v158
	v_rcp_f32_e32 v172, v172
	v_rcp_f32_e32 v173, v173
	v_pk_mul_f32 v[168:169], v[158:159], v[208:209] op_sel_hi:[0,1]
	v_pk_mul_f32 v[164:165], v[164:165], v[168:169]
	v_pk_mul_f32 v[172:173], v[94:95], v[172:173]
	v_cvt_pk_bf16_f32 v168, v164, v165
	v_lshlrev_b32_e32 v164, 16, v159
	v_and_b32_e32 v165, 0xffff0000, v159
	v_pk_mul_f32 v[164:165], v[158:159], v[164:165] op_sel_hi:[0,1]
	v_pk_mul_f32 v[164:165], v[170:171], v[164:165]
	v_pk_mul_f32 v[170:171], v[122:123], s[64:65] op_sel_hi:[1,0]
	v_cvt_pk_bf16_f32 v169, v164, v165
	v_exp_f32_e32 v170, v170
	v_exp_f32_e32 v171, v171
	v_lshlrev_b32_e32 v164, 16, v160
	v_and_b32_e32 v165, 0xffff0000, v160
	v_pk_mul_f32 v[164:165], v[158:159], v[164:165] op_sel_hi:[0,1]
	v_pk_add_f32 v[170:171], v[170:171], 1.0 op_sel_hi:[1,0]
	v_lshlrev_b32_e32 v160, 16, v161
	v_rcp_f32_e32 v170, v170
	v_rcp_f32_e32 v171, v171
	v_and_b32_e32 v161, 0xffff0000, v161
	v_pk_mul_f32 v[160:161], v[158:159], v[160:161] op_sel_hi:[0,1]
	v_pk_mul_f32 v[172:173], v[172:173], v[142:143]
	v_pk_mul_f32 v[170:171], v[122:123], v[170:171]
	s_nop 0
	v_pk_mul_f32 v[170:171], v[170:171], v[138:139]
	s_nop 0
	v_pk_mul_f32 v[164:165], v[170:171], v[164:165]
	s_nop 0
	v_cvt_pk_bf16_f32 v170, v164, v165
	v_pk_mul_f32 v[164:165], v[124:125], s[64:65] op_sel_hi:[1,0]
	s_nop 0
	v_exp_f32_e32 v164, v164
	v_exp_f32_e32 v165, v165
	s_nop 0
	v_pk_add_f32 v[164:165], v[164:165], 1.0 op_sel_hi:[1,0]
	s_nop 0
	v_rcp_f32_e32 v164, v164
	v_rcp_f32_e32 v165, v165
	s_nop 0
	v_pk_mul_f32 v[164:165], v[124:125], v[164:165]
	s_nop 0
	v_pk_mul_f32 v[164:165], v[164:165], v[140:141]
	s_nop 0
	v_pk_mul_f32 v[160:161], v[164:165], v[160:161]
	v_lshlrev_b32_e32 v164, 16, v154
	v_cvt_pk_bf16_f32 v171, v160, v161
	v_lshl_add_u64 v[160:161], s[20:21], 0, v[204:205]
	v_lshl_add_u64 v[160:161], v[160:161], 0, v[190:191]
	global_store_dwordx4 v[160:161], v[168:171], off
	v_and_b32_e32 v165, 0xffff0000, v154
	v_pk_mul_f32 v[164:165], v[158:159], v[164:165] op_sel_hi:[0,1]
	v_pk_mul_f32 v[168:169], v[118:119], s[64:65] op_sel_hi:[1,0]
	s_nop 0
	v_exp_f32_e32 v168, v168
	v_exp_f32_e32 v169, v169
	s_nop 0
	v_pk_add_f32 v[168:169], v[168:169], 1.0 op_sel_hi:[1,0]
	s_nop 0
	v_rcp_f32_e32 v168, v168
	v_rcp_f32_e32 v169, v169
	s_nop 0
	v_pk_mul_f32 v[168:169], v[118:119], v[168:169]
	s_nop 0
	v_pk_mul_f32 v[168:169], v[168:169], v[134:135]
	s_nop 0
	v_pk_mul_f32 v[164:165], v[168:169], v[164:165]
	v_pk_mul_f32 v[168:169], v[120:121], s[64:65] op_sel_hi:[1,0]
	v_cvt_pk_bf16_f32 v154, v164, v165
	v_exp_f32_e32 v168, v168
	v_exp_f32_e32 v169, v169
	v_lshlrev_b32_e32 v164, 16, v155
	v_and_b32_e32 v165, 0xffff0000, v155
	v_pk_mul_f32 v[164:165], v[158:159], v[164:165] op_sel_hi:[0,1]
	v_pk_add_f32 v[168:169], v[168:169], 1.0 op_sel_hi:[1,0]
	s_nop 0
	v_rcp_f32_e32 v168, v168
	v_rcp_f32_e32 v169, v169
	s_nop 0
	v_pk_mul_f32 v[168:169], v[120:121], v[168:169]
	s_nop 0
	v_pk_mul_f32 v[168:169], v[168:169], v[136:137]
	s_nop 0
	v_pk_mul_f32 v[164:165], v[168:169], v[164:165]
	v_pk_mul_f32 v[168:169], v[114:115], s[64:65] op_sel_hi:[1,0]
	v_cvt_pk_bf16_f32 v155, v164, v165
	v_exp_f32_e32 v168, v168
	v_exp_f32_e32 v169, v169
	v_lshlrev_b32_e32 v164, 16, v156
	v_and_b32_e32 v165, 0xffff0000, v156
	v_pk_mul_f32 v[164:165], v[158:159], v[164:165] op_sel_hi:[0,1]
	v_pk_add_f32 v[168:169], v[168:169], 1.0 op_sel_hi:[1,0]
	s_nop 0
	v_rcp_f32_e32 v168, v168
	v_rcp_f32_e32 v169, v169
	s_nop 0
	v_pk_mul_f32 v[168:169], v[114:115], v[168:169]
	s_nop 0
	v_pk_mul_f32 v[168:169], v[168:169], v[130:131]
	s_nop 0
	v_pk_mul_f32 v[164:165], v[168:169], v[164:165]
	v_pk_mul_f32 v[168:169], v[116:117], s[64:65] op_sel_hi:[1,0]
	v_cvt_pk_bf16_f32 v156, v164, v165
	v_exp_f32_e32 v168, v168
	v_exp_f32_e32 v169, v169
	v_lshlrev_b32_e32 v164, 16, v157
	v_and_b32_e32 v165, 0xffff0000, v157
	v_pk_mul_f32 v[158:159], v[158:159], v[164:165] op_sel_hi:[0,1]
	v_pk_add_f32 v[168:169], v[168:169], 1.0 op_sel_hi:[1,0]
	s_nop 0
	v_rcp_f32_e32 v168, v168
	v_rcp_f32_e32 v169, v169
	s_nop 0
	v_pk_mul_f32 v[168:169], v[116:117], v[168:169]
	s_nop 0
	v_pk_mul_f32 v[164:165], v[168:169], v[132:133]
	s_nop 0
	v_pk_mul_f32 v[158:159], v[164:165], v[158:159]
	s_nop 0
	v_cvt_pk_bf16_f32 v157, v158, v159
	v_pk_mul_f32 v[158:159], v[110:111], s[64:65] op_sel_hi:[1,0]
	global_store_dwordx4 v[160:161], v[154:157], off offset:256
	v_exp_f32_e32 v158, v158
	v_exp_f32_e32 v159, v159
	s_waitcnt vmcnt(8)
	v_fmamk_f32 v154, v166, 0x3b800000, v229
	v_rsq_f32_e32 v154, v154
	v_lshlrev_b32_e32 v156, 16, v150
	v_pk_add_f32 v[158:159], v[158:159], 1.0 op_sel_hi:[1,0]
	v_and_b32_e32 v157, 0xffff0000, v150
	v_rcp_f32_e32 v158, v158
	v_rcp_f32_e32 v159, v159
	v_pk_mul_f32 v[156:157], v[154:155], v[156:157] op_sel_hi:[0,1]
	v_lshlrev_b32_e32 v150, 16, v151
	v_and_b32_e32 v151, 0xffff0000, v151
	v_pk_mul_f32 v[158:159], v[110:111], v[158:159]
	v_pk_mul_f32 v[150:151], v[154:155], v[150:151] op_sel_hi:[0,1]
	v_pk_mul_f32 v[158:159], v[158:159], v[142:143]
	s_nop 0
	v_pk_mul_f32 v[156:157], v[158:159], v[156:157]
	v_pk_mul_f32 v[158:159], v[112:113], s[64:65] op_sel_hi:[1,0]
	v_cvt_pk_bf16_f32 v156, v156, v157
	v_exp_f32_e32 v158, v158
	v_exp_f32_e32 v159, v159
	s_nop 0
	v_pk_add_f32 v[158:159], v[158:159], 1.0 op_sel_hi:[1,0]
	s_nop 0
	v_rcp_f32_e32 v158, v158
	v_rcp_f32_e32 v159, v159
	s_nop 0
	v_pk_mul_f32 v[158:159], v[112:113], v[158:159]
	s_nop 0
	v_pk_mul_f32 v[158:159], v[158:159], v[144:145]
	s_nop 0
	v_pk_mul_f32 v[150:151], v[158:159], v[150:151]
	v_pk_mul_f32 v[158:159], v[106:107], s[64:65] op_sel_hi:[1,0]
	v_cvt_pk_bf16_f32 v157, v150, v151
	v_exp_f32_e32 v158, v158
	v_exp_f32_e32 v159, v159
	v_lshlrev_b32_e32 v150, 16, v152
	v_and_b32_e32 v151, 0xffff0000, v152
	v_pk_mul_f32 v[150:151], v[154:155], v[150:151] op_sel_hi:[0,1]
	v_pk_add_f32 v[158:159], v[158:159], 1.0 op_sel_hi:[1,0]
	s_nop 0
	v_rcp_f32_e32 v158, v158
	v_rcp_f32_e32 v159, v159
	s_nop 0
	v_pk_mul_f32 v[158:159], v[106:107], v[158:159]
	s_nop 0
	v_pk_mul_f32 v[158:159], v[158:159], v[138:139]
	s_nop 0
	v_pk_mul_f32 v[150:151], v[158:159], v[150:151]
	s_nop 0
	v_cvt_pk_bf16_f32 v158, v150, v151
	v_lshlrev_b32_e32 v150, 16, v153
	v_and_b32_e32 v151, 0xffff0000, v153
	v_pk_mul_f32 v[152:153], v[108:109], s[64:65] op_sel_hi:[1,0]
	v_pk_mul_f32 v[150:151], v[154:155], v[150:151] op_sel_hi:[0,1]
	v_exp_f32_e32 v152, v152
	v_exp_f32_e32 v153, v153
	s_nop 0
	v_pk_add_f32 v[152:153], v[152:153], 1.0 op_sel_hi:[1,0]
	s_nop 0
	v_rcp_f32_e32 v152, v152
	v_rcp_f32_e32 v153, v153
	s_nop 0
	v_pk_mul_f32 v[152:153], v[108:109], v[152:153]
	s_nop 0
	v_pk_mul_f32 v[152:153], v[152:153], v[140:141]
	s_nop 0
	v_pk_mul_f32 v[150:151], v[152:153], v[150:151]
	v_lshlrev_b32_e32 v152, 16, v146
	v_cvt_pk_bf16_f32 v159, v150, v151
	v_lshl_add_u64 v[150:151], s[20:21], 0, v[202:203]
	v_lshl_add_u64 v[150:151], v[150:151], 0, v[190:191]
	global_store_dwordx4 v[150:151], v[156:159], off
	v_and_b32_e32 v153, 0xffff0000, v146
	v_pk_mul_f32 v[152:153], v[154:155], v[152:153] op_sel_hi:[0,1]
	v_pk_mul_f32 v[156:157], v[102:103], s[64:65] op_sel_hi:[1,0]
	s_nop 0
	v_exp_f32_e32 v156, v156
	v_exp_f32_e32 v157, v157
	s_nop 0
	v_pk_add_f32 v[156:157], v[156:157], 1.0 op_sel_hi:[1,0]
	s_nop 0
	v_rcp_f32_e32 v156, v156
	v_rcp_f32_e32 v157, v157
	s_nop 0
	v_pk_mul_f32 v[156:157], v[102:103], v[156:157]
	s_nop 0
	v_pk_mul_f32 v[156:157], v[156:157], v[134:135]
	s_nop 0
	v_pk_mul_f32 v[152:153], v[156:157], v[152:153]
	v_pk_mul_f32 v[156:157], v[104:105], s[64:65] op_sel_hi:[1,0]
	v_cvt_pk_bf16_f32 v146, v152, v153
	v_exp_f32_e32 v156, v156
	v_exp_f32_e32 v157, v157
	v_lshlrev_b32_e32 v152, 16, v147
	v_and_b32_e32 v153, 0xffff0000, v147
	v_pk_mul_f32 v[152:153], v[154:155], v[152:153] op_sel_hi:[0,1]
	v_pk_add_f32 v[156:157], v[156:157], 1.0 op_sel_hi:[1,0]
	s_nop 0
	v_rcp_f32_e32 v156, v156
	v_rcp_f32_e32 v157, v157
	s_nop 0
	v_pk_mul_f32 v[156:157], v[104:105], v[156:157]
	s_nop 0
	v_pk_mul_f32 v[156:157], v[156:157], v[136:137]
	s_nop 0
	v_pk_mul_f32 v[152:153], v[156:157], v[152:153]
	v_pk_mul_f32 v[156:157], v[98:99], s[64:65] op_sel_hi:[1,0]
	v_cvt_pk_bf16_f32 v147, v152, v153
	v_exp_f32_e32 v156, v156
	v_exp_f32_e32 v157, v157
	v_lshlrev_b32_e32 v152, 16, v148
	v_and_b32_e32 v153, 0xffff0000, v148
	v_pk_mul_f32 v[152:153], v[154:155], v[152:153] op_sel_hi:[0,1]
	v_pk_add_f32 v[156:157], v[156:157], 1.0 op_sel_hi:[1,0]
	s_nop 0
	v_rcp_f32_e32 v156, v156
	v_rcp_f32_e32 v157, v157
	s_nop 0
	v_pk_mul_f32 v[156:157], v[98:99], v[156:157]
	s_nop 0
	v_pk_mul_f32 v[156:157], v[156:157], v[130:131]
	s_nop 0
	v_pk_mul_f32 v[152:153], v[156:157], v[152:153]
	v_pk_mul_f32 v[156:157], v[100:101], s[64:65] op_sel_hi:[1,0]
	v_cvt_pk_bf16_f32 v148, v152, v153
	v_exp_f32_e32 v156, v156
	v_exp_f32_e32 v157, v157
	v_lshlrev_b32_e32 v152, 16, v149
	v_and_b32_e32 v153, 0xffff0000, v149
	v_pk_mul_f32 v[152:153], v[154:155], v[152:153] op_sel_hi:[0,1]
	v_pk_add_f32 v[156:157], v[156:157], 1.0 op_sel_hi:[1,0]
	s_nop 0
	v_rcp_f32_e32 v156, v156
	v_rcp_f32_e32 v157, v157
	s_nop 0
	v_pk_mul_f32 v[156:157], v[100:101], v[156:157]
	s_nop 0
	v_pk_mul_f32 v[154:155], v[156:157], v[132:133]
	s_nop 0
	v_pk_mul_f32 v[152:153], v[154:155], v[152:153]
	s_nop 0
	v_cvt_pk_bf16_f32 v149, v152, v153
	global_store_dwordx4 v[150:151], v[146:149], off offset:256
	s_waitcnt vmcnt(4)
	v_fmamk_f32 v160, v238, 0x3b800000, v229
	v_or_b32_e32 v146, 32, v186
	v_ashrrev_i32_e32 v147, 31, v146
	v_lshlrev_b64 v[164:165], 12, v[146:147]
	v_lshl_add_u64 v[146:147], v[200:201], 0, v[164:165]
	global_load_dwordx4 v[166:169], v[146:147], off
	global_load_dwordx4 v[154:157], v[146:147], off offset:256
	v_mov_b32_e32 v161, v239
	v_rsq_f32_e32 v160, v160
	v_or_b32_e32 v146, 48, v186
	v_ashrrev_i32_e32 v147, 31, v146
	v_lshlrev_b64 v[158:159], 12, v[146:147]
	v_lshl_add_u64 v[146:147], v[200:201], 0, v[158:159]
	global_load_dwordx4 v[150:153], v[146:147], off
	s_nop 0
	global_load_dwordx4 v[146:149], v[146:147], off offset:256
	v_lshl_add_u64 v[164:165], s[20:21], 0, v[164:165]
	v_lshl_add_u64 v[164:165], v[164:165], 0, v[190:191]
	s_waitcnt vmcnt(3)
	v_lshlrev_b32_e32 v170, 16, v166
	v_and_b32_e32 v171, 0xffff0000, v166
	s_waitcnt vmcnt(2)
	v_pk_mul_f32 v[170:171], v[160:161], v[170:171] op_sel_hi:[0,1]
	v_pk_mul_f32 v[170:171], v[172:173], v[170:171]
	v_pk_mul_f32 v[172:173], v[96:97], s[64:65] op_sel_hi:[1,0]
	v_cvt_pk_bf16_f32 v166, v170, v171
	v_exp_f32_e32 v172, v172
	v_exp_f32_e32 v173, v173
	v_lshlrev_b32_e32 v170, 16, v167
	v_and_b32_e32 v171, 0xffff0000, v167
	v_pk_mul_f32 v[170:171], v[160:161], v[170:171] op_sel_hi:[0,1]
	v_pk_add_f32 v[172:173], v[172:173], 1.0 op_sel_hi:[1,0]
	s_nop 0
	v_rcp_f32_e32 v172, v172
	v_rcp_f32_e32 v173, v173
	s_nop 0
	v_pk_mul_f32 v[172:173], v[96:97], v[172:173]
	s_nop 0
	v_pk_mul_f32 v[172:173], v[172:173], v[144:145]
	s_nop 0
	v_pk_mul_f32 v[170:171], v[172:173], v[170:171]
	v_pk_mul_f32 v[172:173], v[90:91], s[64:65] op_sel_hi:[1,0]
	v_cvt_pk_bf16_f32 v167, v170, v171
	v_exp_f32_e32 v172, v172
	v_exp_f32_e32 v173, v173
	v_lshlrev_b32_e32 v170, 16, v168
	v_and_b32_e32 v171, 0xffff0000, v168
	v_pk_mul_f32 v[170:171], v[160:161], v[170:171] op_sel_hi:[0,1]
	v_pk_add_f32 v[172:173], v[172:173], 1.0 op_sel_hi:[1,0]
	s_nop 0
	v_rcp_f32_e32 v172, v172
	v_rcp_f32_e32 v173, v173
	s_nop 0
	v_pk_mul_f32 v[172:173], v[90:91], v[172:173]
	s_nop 0
	v_pk_mul_f32 v[172:173], v[172:173], v[138:139]
	s_nop 0
	v_pk_mul_f32 v[170:171], v[172:173], v[170:171]
	v_pk_mul_f32 v[172:173], v[92:93], s[64:65] op_sel_hi:[1,0]
	v_cvt_pk_bf16_f32 v168, v170, v171
	v_exp_f32_e32 v172, v172
	v_exp_f32_e32 v173, v173
	v_lshlrev_b32_e32 v170, 16, v169
	v_and_b32_e32 v171, 0xffff0000, v169
	v_pk_mul_f32 v[170:171], v[160:161], v[170:171] op_sel_hi:[0,1]
	v_pk_add_f32 v[172:173], v[172:173], 1.0 op_sel_hi:[1,0]
	s_nop 0
	v_rcp_f32_e32 v172, v172
	v_rcp_f32_e32 v173, v173
	s_nop 0
	v_pk_mul_f32 v[172:173], v[92:93], v[172:173]
	s_nop 0
	v_pk_mul_f32 v[172:173], v[172:173], v[140:141]
	s_nop 0
	v_pk_mul_f32 v[170:171], v[172:173], v[170:171]
	v_pk_mul_f32 v[172:173], v[62:63], s[64:65] op_sel_hi:[1,0]
	v_cvt_pk_bf16_f32 v169, v170, v171
	global_store_dwordx4 v[164:165], v[166:169], off
	v_exp_f32_e32 v172, v172
	v_exp_f32_e32 v173, v173
	v_pk_mul_f32 v[168:169], v[86:87], s[64:65] op_sel_hi:[1,0]
	v_lshlrev_b32_e32 v166, 16, v154
	v_exp_f32_e32 v168, v168
	v_exp_f32_e32 v169, v169
	v_and_b32_e32 v167, 0xffff0000, v154
	v_pk_mul_f32 v[166:167], v[160:161], v[166:167] op_sel_hi:[0,1]
	v_pk_add_f32 v[172:173], v[172:173], 1.0 op_sel_hi:[1,0]
	v_pk_add_f32 v[168:169], v[168:169], 1.0 op_sel_hi:[1,0]
	v_rcp_f32_e32 v172, v172
	v_rcp_f32_e32 v168, v168
	v_rcp_f32_e32 v169, v169
	v_rcp_f32_e32 v173, v173
	v_pk_mul_f32 v[168:169], v[86:87], v[168:169]
	s_nop 0
	v_pk_mul_f32 v[168:169], v[168:169], v[134:135]
	v_pk_mul_f32 v[172:173], v[62:63], v[172:173]
	v_pk_mul_f32 v[166:167], v[168:169], v[166:167]
	v_pk_mul_f32 v[168:169], v[88:89], s[64:65] op_sel_hi:[1,0]
	v_cvt_pk_bf16_f32 v154, v166, v167
	v_exp_f32_e32 v168, v168
	v_exp_f32_e32 v169, v169
	v_lshlrev_b32_e32 v166, 16, v155
	v_and_b32_e32 v167, 0xffff0000, v155
	v_pk_mul_f32 v[166:167], v[160:161], v[166:167] op_sel_hi:[0,1]
	v_pk_add_f32 v[168:169], v[168:169], 1.0 op_sel_hi:[1,0]
	v_pk_mul_f32 v[172:173], v[172:173], v[142:143]
	v_rcp_f32_e32 v168, v168
	v_rcp_f32_e32 v169, v169
	s_nop 0
	v_pk_mul_f32 v[168:169], v[88:89], v[168:169]
	s_nop 0
	v_pk_mul_f32 v[168:169], v[168:169], v[136:137]
	s_nop 0
	v_pk_mul_f32 v[166:167], v[168:169], v[166:167]
	v_pk_mul_f32 v[168:169], v[82:83], s[64:65] op_sel_hi:[1,0]
	v_cvt_pk_bf16_f32 v155, v166, v167
	v_exp_f32_e32 v168, v168
	v_exp_f32_e32 v169, v169
	v_lshlrev_b32_e32 v166, 16, v156
	v_and_b32_e32 v167, 0xffff0000, v156
	v_pk_mul_f32 v[166:167], v[160:161], v[166:167] op_sel_hi:[0,1]
	v_pk_add_f32 v[168:169], v[168:169], 1.0 op_sel_hi:[1,0]
	s_nop 0
	v_rcp_f32_e32 v168, v168
	v_rcp_f32_e32 v169, v169
	s_nop 0
	v_pk_mul_f32 v[168:169], v[82:83], v[168:169]
	s_nop 0
	v_pk_mul_f32 v[168:169], v[168:169], v[130:131]
	s_nop 0
	v_pk_mul_f32 v[166:167], v[168:169], v[166:167]
	v_pk_mul_f32 v[168:169], v[84:85], s[64:65] op_sel_hi:[1,0]
	v_cvt_pk_bf16_f32 v156, v166, v167
	v_exp_f32_e32 v168, v168
	v_exp_f32_e32 v169, v169
	v_lshlrev_b32_e32 v166, 16, v157
	v_and_b32_e32 v167, 0xffff0000, v157
	v_pk_mul_f32 v[166:167], v[160:161], v[166:167] op_sel_hi:[0,1]
	v_pk_add_f32 v[168:169], v[168:169], 1.0 op_sel_hi:[1,0]
	s_nop 0
	v_rcp_f32_e32 v168, v168
	v_rcp_f32_e32 v169, v169
	s_nop 0
	v_pk_mul_f32 v[168:169], v[84:85], v[168:169]
	s_nop 0
	v_pk_mul_f32 v[168:169], v[168:169], v[132:133]
	s_nop 0
	v_pk_mul_f32 v[166:167], v[168:169], v[166:167]
	s_nop 0
	v_cvt_pk_bf16_f32 v157, v166, v167
	global_store_dwordx4 v[164:165], v[154:157], off offset:256
	s_nop 1
	v_fmamk_f32 v154, v161, 0x3b800000, v229
	v_pk_mul_f32 v[160:161], v[78:79], s[64:65] op_sel_hi:[1,0]
	v_rsq_f32_e32 v154, v154
	v_exp_f32_e32 v160, v160
	v_exp_f32_e32 v161, v161
	s_waitcnt vmcnt(3)
	v_lshlrev_b32_e32 v156, 16, v150
	v_and_b32_e32 v157, 0xffff0000, v150
	v_pk_mul_f32 v[156:157], v[154:155], v[156:157] op_sel_hi:[0,1]
	v_pk_add_f32 v[160:161], v[160:161], 1.0 op_sel_hi:[1,0]
	v_lshlrev_b32_e32 v150, 16, v151
	v_rcp_f32_e32 v160, v160
	v_rcp_f32_e32 v161, v161
	v_and_b32_e32 v151, 0xffff0000, v151
	v_pk_mul_f32 v[150:151], v[154:155], v[150:151] op_sel_hi:[0,1]
	v_pk_mul_f32 v[160:161], v[78:79], v[160:161]
	s_nop 0
	v_pk_mul_f32 v[160:161], v[160:161], v[142:143]
	s_nop 0
	v_pk_mul_f32 v[156:157], v[160:161], v[156:157]
	s_nop 0
	v_cvt_pk_bf16_f32 v164, v156, v157
	v_pk_mul_f32 v[156:157], v[80:81], s[64:65] op_sel_hi:[1,0]
	s_nop 0
	v_exp_f32_e32 v156, v156
	v_exp_f32_e32 v157, v157
	s_nop 0
	v_pk_add_f32 v[156:157], v[156:157], 1.0 op_sel_hi:[1,0]
	s_nop 0
	v_rcp_f32_e32 v156, v156
	v_rcp_f32_e32 v157, v157
	s_nop 0
	v_pk_mul_f32 v[156:157], v[80:81], v[156:157]
	s_nop 0
	v_pk_mul_f32 v[156:157], v[156:157], v[144:145]
	s_nop 0
	v_pk_mul_f32 v[150:151], v[156:157], v[150:151]
	v_pk_mul_f32 v[156:157], v[74:75], s[64:65] op_sel_hi:[1,0]
	v_cvt_pk_bf16_f32 v165, v150, v151
	v_exp_f32_e32 v156, v156
	v_exp_f32_e32 v157, v157
	v_lshlrev_b32_e32 v150, 16, v152
	v_and_b32_e32 v151, 0xffff0000, v152
	v_pk_mul_f32 v[150:151], v[154:155], v[150:151] op_sel_hi:[0,1]
	v_pk_add_f32 v[156:157], v[156:157], 1.0 op_sel_hi:[1,0]
	s_nop 0
	v_rcp_f32_e32 v156, v156
	v_rcp_f32_e32 v157, v157
	s_nop 0
	v_pk_mul_f32 v[156:157], v[74:75], v[156:157]
	s_nop 0
	v_pk_mul_f32 v[156:157], v[156:157], v[138:139]
	s_nop 0
	v_pk_mul_f32 v[150:151], v[156:157], v[150:151]
	v_pk_mul_f32 v[156:157], v[70:71], s[64:65] op_sel_hi:[1,0]
	v_cvt_pk_bf16_f32 v166, v150, v151
	v_lshlrev_b32_e32 v150, 16, v153
	v_and_b32_e32 v151, 0xffff0000, v153
	v_pk_mul_f32 v[152:153], v[76:77], s[64:65] op_sel_hi:[1,0]
	v_exp_f32_e32 v156, v156
	v_exp_f32_e32 v152, v152
	v_exp_f32_e32 v153, v153
	v_exp_f32_e32 v157, v157
	v_pk_mul_f32 v[150:151], v[154:155], v[150:151] op_sel_hi:[0,1]
	v_pk_add_f32 v[152:153], v[152:153], 1.0 op_sel_hi:[1,0]
	s_nop 0
	v_rcp_f32_e32 v152, v152
	v_rcp_f32_e32 v153, v153
	v_pk_add_f32 v[156:157], v[156:157], 1.0 op_sel_hi:[1,0]
	v_pk_mul_f32 v[152:153], v[76:77], v[152:153]
	v_rcp_f32_e32 v156, v156
	v_rcp_f32_e32 v157, v157
	v_pk_mul_f32 v[152:153], v[152:153], v[140:141]
	v_pk_mul_f32 v[156:157], v[70:71], v[156:157]
	v_pk_mul_f32 v[150:151], v[152:153], v[150:151]
	s_waitcnt vmcnt(2)
	v_lshlrev_b32_e32 v152, 16, v146
	v_and_b32_e32 v153, 0xffff0000, v146
	v_pk_mul_f32 v[152:153], v[154:155], v[152:153] op_sel_hi:[0,1]
	v_pk_mul_f32 v[156:157], v[156:157], v[134:135]
	v_cvt_pk_bf16_f32 v167, v150, v151
	v_pk_mul_f32 v[152:153], v[156:157], v[152:153]
	v_pk_mul_f32 v[156:157], v[72:73], s[64:65] op_sel_hi:[1,0]
	v_cvt_pk_bf16_f32 v146, v152, v153
	v_exp_f32_e32 v156, v156
	v_exp_f32_e32 v157, v157
	v_lshlrev_b32_e32 v152, 16, v147
	v_and_b32_e32 v153, 0xffff0000, v147
	v_pk_mul_f32 v[152:153], v[154:155], v[152:153] op_sel_hi:[0,1]
	v_pk_add_f32 v[156:157], v[156:157], 1.0 op_sel_hi:[1,0]
	v_lshl_add_u64 v[150:151], s[20:21], 0, v[158:159]
	v_rcp_f32_e32 v156, v156
	v_rcp_f32_e32 v157, v157
	v_lshl_add_u64 v[150:151], v[150:151], 0, v[190:191]
	global_store_dwordx4 v[150:151], v[164:167], off
	v_pk_mul_f32 v[156:157], v[72:73], v[156:157]
	s_nop 0
	v_pk_mul_f32 v[156:157], v[156:157], v[136:137]
	s_nop 0
	v_pk_mul_f32 v[152:153], v[156:157], v[152:153]
	v_pk_mul_f32 v[156:157], v[66:67], s[64:65] op_sel_hi:[1,0]
	v_cvt_pk_bf16_f32 v147, v152, v153
	v_exp_f32_e32 v156, v156
	v_exp_f32_e32 v157, v157
	v_lshlrev_b32_e32 v152, 16, v148
	v_and_b32_e32 v153, 0xffff0000, v148
	v_pk_mul_f32 v[152:153], v[154:155], v[152:153] op_sel_hi:[0,1]
	v_pk_add_f32 v[156:157], v[156:157], 1.0 op_sel_hi:[1,0]
	s_nop 0
	v_rcp_f32_e32 v156, v156
	v_rcp_f32_e32 v157, v157
	s_nop 0
	v_pk_mul_f32 v[156:157], v[66:67], v[156:157]
	s_nop 0
	v_pk_mul_f32 v[156:157], v[156:157], v[130:131]
	s_nop 0
	v_pk_mul_f32 v[152:153], v[156:157], v[152:153]
	v_pk_mul_f32 v[156:157], v[68:69], s[64:65] op_sel_hi:[1,0]
	v_cvt_pk_bf16_f32 v148, v152, v153
	v_exp_f32_e32 v156, v156
	v_exp_f32_e32 v157, v157
	v_lshlrev_b32_e32 v152, 16, v149
	v_and_b32_e32 v153, 0xffff0000, v149
	v_pk_mul_f32 v[152:153], v[154:155], v[152:153] op_sel_hi:[0,1]
	v_pk_add_f32 v[156:157], v[156:157], 1.0 op_sel_hi:[1,0]
	s_nop 0
	v_rcp_f32_e32 v156, v156
	v_rcp_f32_e32 v157, v157
	s_nop 0
	v_pk_mul_f32 v[156:157], v[68:69], v[156:157]
	s_nop 0
	v_pk_mul_f32 v[154:155], v[156:157], v[132:133]
	s_nop 0
	v_pk_mul_f32 v[152:153], v[154:155], v[152:153]
	s_nop 0
	v_cvt_pk_bf16_f32 v149, v152, v153
	global_store_dwordx4 v[150:151], v[146:149], off offset:256
	s_waitcnt vmcnt(4)
	v_fmamk_f32 v160, v240, 0x3b800000, v229
	v_add_u32_e32 v146, 0x80, v186
	v_ashrrev_i32_e32 v147, 31, v146
	v_lshlrev_b64 v[164:165], 12, v[146:147]
	v_lshl_add_u64 v[146:147], v[200:201], 0, v[164:165]
	global_load_dwordx4 v[166:169], v[146:147], off
	global_load_dwordx4 v[154:157], v[146:147], off offset:256
	v_mov_b32_e32 v161, v241
	v_rsq_f32_e32 v160, v160
	v_add_u32_e32 v146, 0x90, v186
	v_ashrrev_i32_e32 v147, 31, v146
	v_lshlrev_b64 v[158:159], 12, v[146:147]
	v_lshl_add_u64 v[146:147], v[200:201], 0, v[158:159]
	global_load_dwordx4 v[150:153], v[146:147], off
	s_nop 0
	global_load_dwordx4 v[146:149], v[146:147], off offset:256
	v_lshl_add_u64 v[164:165], s[20:21], 0, v[164:165]
	v_lshl_add_u64 v[164:165], v[164:165], 0, v[190:191]
	s_waitcnt vmcnt(3)
	v_lshlrev_b32_e32 v170, 16, v166
	v_and_b32_e32 v171, 0xffff0000, v166
	s_waitcnt vmcnt(2)
	v_pk_mul_f32 v[170:171], v[160:161], v[170:171] op_sel_hi:[0,1]
	v_pk_mul_f32 v[170:171], v[172:173], v[170:171]
	v_pk_mul_f32 v[172:173], v[64:65], s[64:65] op_sel_hi:[1,0]
	v_cvt_pk_bf16_f32 v166, v170, v171
	v_exp_f32_e32 v172, v172
	v_exp_f32_e32 v173, v173
	v_lshlrev_b32_e32 v170, 16, v167
	v_and_b32_e32 v171, 0xffff0000, v167
	v_pk_mul_f32 v[170:171], v[160:161], v[170:171] op_sel_hi:[0,1]
	v_pk_add_f32 v[172:173], v[172:173], 1.0 op_sel_hi:[1,0]
	s_nop 0
	v_rcp_f32_e32 v172, v172
	v_rcp_f32_e32 v173, v173
	s_nop 0
	v_pk_mul_f32 v[172:173], v[64:65], v[172:173]
	s_nop 0
	v_pk_mul_f32 v[172:173], v[172:173], v[144:145]
	s_nop 0
	v_pk_mul_f32 v[170:171], v[172:173], v[170:171]
	v_pk_mul_f32 v[172:173], v[58:59], s[64:65] op_sel_hi:[1,0]
	v_cvt_pk_bf16_f32 v167, v170, v171
	v_exp_f32_e32 v172, v172
	v_exp_f32_e32 v173, v173
	v_lshlrev_b32_e32 v170, 16, v168
	v_and_b32_e32 v171, 0xffff0000, v168
	v_pk_mul_f32 v[170:171], v[160:161], v[170:171] op_sel_hi:[0,1]
	v_pk_add_f32 v[172:173], v[172:173], 1.0 op_sel_hi:[1,0]
	s_nop 0
	v_rcp_f32_e32 v172, v172
	v_rcp_f32_e32 v173, v173
	s_nop 0
	v_pk_mul_f32 v[172:173], v[58:59], v[172:173]
	s_nop 0
	v_pk_mul_f32 v[172:173], v[172:173], v[138:139]
	s_nop 0
	v_pk_mul_f32 v[170:171], v[172:173], v[170:171]
	v_pk_mul_f32 v[172:173], v[60:61], s[64:65] op_sel_hi:[1,0]
	v_cvt_pk_bf16_f32 v168, v170, v171
	v_exp_f32_e32 v172, v172
	v_exp_f32_e32 v173, v173
	v_lshlrev_b32_e32 v170, 16, v169
	v_and_b32_e32 v171, 0xffff0000, v169
	v_pk_mul_f32 v[170:171], v[160:161], v[170:171] op_sel_hi:[0,1]
	v_pk_add_f32 v[172:173], v[172:173], 1.0 op_sel_hi:[1,0]
	s_nop 0
	v_rcp_f32_e32 v172, v172
	v_rcp_f32_e32 v173, v173
	s_nop 0
	v_pk_mul_f32 v[172:173], v[60:61], v[172:173]
	s_nop 0
	v_pk_mul_f32 v[172:173], v[172:173], v[140:141]
	s_nop 0
	v_pk_mul_f32 v[170:171], v[172:173], v[170:171]
	s_nop 0
	v_cvt_pk_bf16_f32 v169, v170, v171
	global_store_dwordx4 v[164:165], v[166:169], off
	v_pk_mul_f32 v[170:171], v[30:31], s[64:65] op_sel_hi:[1,0]
	s_nop 0
	v_pk_mul_f32 v[168:169], v[54:55], s[64:65] op_sel_hi:[1,0]
	v_lshlrev_b32_e32 v166, 16, v154
	v_exp_f32_e32 v168, v168
	v_exp_f32_e32 v169, v169
	v_and_b32_e32 v167, 0xffff0000, v154
	v_pk_mul_f32 v[166:167], v[160:161], v[166:167] op_sel_hi:[0,1]
	v_exp_f32_e32 v170, v170
	v_pk_add_f32 v[168:169], v[168:169], 1.0 op_sel_hi:[1,0]
	v_exp_f32_e32 v171, v171
	v_rcp_f32_e32 v168, v168
	v_rcp_f32_e32 v169, v169
	v_pk_add_f32 v[170:171], v[170:171], 1.0 op_sel_hi:[1,0]
	s_nop 0
	v_rcp_f32_e32 v170, v170
	v_pk_mul_f32 v[168:169], v[54:55], v[168:169]
	v_rcp_f32_e32 v171, v171
	v_pk_mul_f32 v[168:169], v[168:169], v[134:135]
	v_pk_mul_f32 v[170:171], v[30:31], v[170:171]
	v_pk_mul_f32 v[166:167], v[168:169], v[166:167]
	v_pk_mul_f32 v[168:169], v[56:57], s[64:65] op_sel_hi:[1,0]
	v_cvt_pk_bf16_f32 v154, v166, v167
	v_exp_f32_e32 v168, v168
	v_exp_f32_e32 v169, v169
	v_lshlrev_b32_e32 v166, 16, v155
	v_and_b32_e32 v167, 0xffff0000, v155
	v_pk_mul_f32 v[166:167], v[160:161], v[166:167] op_sel_hi:[0,1]
	v_pk_add_f32 v[168:169], v[168:169], 1.0 op_sel_hi:[1,0]
	v_pk_mul_f32 v[170:171], v[170:171], v[142:143]
	v_rcp_f32_e32 v168, v168
	v_rcp_f32_e32 v169, v169
	s_nop 0
	v_pk_mul_f32 v[168:169], v[56:57], v[168:169]
	s_nop 0
	v_pk_mul_f32 v[168:169], v[168:169], v[136:137]
	s_nop 0
	v_pk_mul_f32 v[166:167], v[168:169], v[166:167]
	v_pk_mul_f32 v[168:169], v[50:51], s[64:65] op_sel_hi:[1,0]
	v_cvt_pk_bf16_f32 v155, v166, v167
	v_exp_f32_e32 v168, v168
	v_exp_f32_e32 v169, v169
	v_lshlrev_b32_e32 v166, 16, v156
	v_and_b32_e32 v167, 0xffff0000, v156
	v_pk_mul_f32 v[166:167], v[160:161], v[166:167] op_sel_hi:[0,1]
	v_pk_add_f32 v[168:169], v[168:169], 1.0 op_sel_hi:[1,0]
	s_nop 0
	v_rcp_f32_e32 v168, v168
	v_rcp_f32_e32 v169, v169
	s_nop 0
	v_pk_mul_f32 v[168:169], v[50:51], v[168:169]
	s_nop 0
	v_pk_mul_f32 v[168:169], v[168:169], v[130:131]
	s_nop 0
	v_pk_mul_f32 v[166:167], v[168:169], v[166:167]
	v_pk_mul_f32 v[168:169], v[52:53], s[64:65] op_sel_hi:[1,0]
	v_cvt_pk_bf16_f32 v156, v166, v167
	v_exp_f32_e32 v168, v168
	v_exp_f32_e32 v169, v169
	v_lshlrev_b32_e32 v166, 16, v157
	v_and_b32_e32 v167, 0xffff0000, v157
	v_pk_mul_f32 v[166:167], v[160:161], v[166:167] op_sel_hi:[0,1]
	v_pk_add_f32 v[168:169], v[168:169], 1.0 op_sel_hi:[1,0]
	s_nop 0
	v_rcp_f32_e32 v168, v168
	v_rcp_f32_e32 v169, v169
	s_nop 0
	v_pk_mul_f32 v[168:169], v[52:53], v[168:169]
	s_nop 0
	v_pk_mul_f32 v[168:169], v[168:169], v[132:133]
	s_nop 0
	v_pk_mul_f32 v[166:167], v[168:169], v[166:167]
	s_nop 0
	v_cvt_pk_bf16_f32 v157, v166, v167
	global_store_dwordx4 v[164:165], v[154:157], off offset:256
	s_nop 1
	v_fmamk_f32 v154, v161, 0x3b800000, v229
	v_pk_mul_f32 v[160:161], v[46:47], s[64:65] op_sel_hi:[1,0]
	v_rsq_f32_e32 v154, v154
	v_exp_f32_e32 v160, v160
	v_exp_f32_e32 v161, v161
	s_waitcnt vmcnt(3)
	v_lshlrev_b32_e32 v156, 16, v150
	v_and_b32_e32 v157, 0xffff0000, v150
	v_pk_mul_f32 v[156:157], v[154:155], v[156:157] op_sel_hi:[0,1]
	v_pk_add_f32 v[160:161], v[160:161], 1.0 op_sel_hi:[1,0]
	v_lshlrev_b32_e32 v150, 16, v151
	v_rcp_f32_e32 v160, v160
	v_rcp_f32_e32 v161, v161
	v_and_b32_e32 v151, 0xffff0000, v151
	v_pk_mul_f32 v[150:151], v[154:155], v[150:151] op_sel_hi:[0,1]
	v_pk_mul_f32 v[160:161], v[46:47], v[160:161]
	s_nop 0
	v_pk_mul_f32 v[160:161], v[160:161], v[142:143]
	s_nop 0
	v_pk_mul_f32 v[156:157], v[160:161], v[156:157]
	s_nop 0
	v_cvt_pk_bf16_f32 v164, v156, v157
	v_pk_mul_f32 v[156:157], v[48:49], s[64:65] op_sel_hi:[1,0]
	s_nop 0
	v_exp_f32_e32 v156, v156
	v_exp_f32_e32 v157, v157
	s_nop 0
	v_pk_add_f32 v[156:157], v[156:157], 1.0 op_sel_hi:[1,0]
	s_nop 0
	v_rcp_f32_e32 v156, v156
	v_rcp_f32_e32 v157, v157
	s_nop 0
	v_pk_mul_f32 v[156:157], v[48:49], v[156:157]
	s_nop 0
	v_pk_mul_f32 v[156:157], v[156:157], v[144:145]
	s_nop 0
	v_pk_mul_f32 v[150:151], v[156:157], v[150:151]
	v_pk_mul_f32 v[156:157], v[42:43], s[64:65] op_sel_hi:[1,0]
	v_cvt_pk_bf16_f32 v165, v150, v151
	v_exp_f32_e32 v156, v156
	v_exp_f32_e32 v157, v157
	v_lshlrev_b32_e32 v150, 16, v152
	v_and_b32_e32 v151, 0xffff0000, v152
	v_pk_mul_f32 v[150:151], v[154:155], v[150:151] op_sel_hi:[0,1]
	v_pk_add_f32 v[156:157], v[156:157], 1.0 op_sel_hi:[1,0]
	s_nop 0
	v_rcp_f32_e32 v156, v156
	v_rcp_f32_e32 v157, v157
	s_nop 0
	v_pk_mul_f32 v[156:157], v[42:43], v[156:157]
	s_nop 0
	v_pk_mul_f32 v[156:157], v[156:157], v[138:139]
	s_nop 0
	v_pk_mul_f32 v[150:151], v[156:157], v[150:151]
	v_pk_mul_f32 v[156:157], v[38:39], s[64:65] op_sel_hi:[1,0]
	v_cvt_pk_bf16_f32 v166, v150, v151
	v_lshlrev_b32_e32 v150, 16, v153
	v_and_b32_e32 v151, 0xffff0000, v153
	v_pk_mul_f32 v[152:153], v[44:45], s[64:65] op_sel_hi:[1,0]
	v_exp_f32_e32 v156, v156
	v_exp_f32_e32 v152, v152
	v_exp_f32_e32 v153, v153
	v_exp_f32_e32 v157, v157
	v_pk_mul_f32 v[150:151], v[154:155], v[150:151] op_sel_hi:[0,1]
	v_pk_add_f32 v[152:153], v[152:153], 1.0 op_sel_hi:[1,0]
	s_nop 0
	v_rcp_f32_e32 v152, v152
	v_rcp_f32_e32 v153, v153
	v_pk_add_f32 v[156:157], v[156:157], 1.0 op_sel_hi:[1,0]
	v_pk_mul_f32 v[152:153], v[44:45], v[152:153]
	v_rcp_f32_e32 v156, v156
	v_rcp_f32_e32 v157, v157
	v_pk_mul_f32 v[152:153], v[152:153], v[140:141]
	v_pk_mul_f32 v[156:157], v[38:39], v[156:157]
	v_pk_mul_f32 v[150:151], v[152:153], v[150:151]
	s_waitcnt vmcnt(2)
	v_lshlrev_b32_e32 v152, 16, v146
	v_and_b32_e32 v153, 0xffff0000, v146
	v_pk_mul_f32 v[152:153], v[154:155], v[152:153] op_sel_hi:[0,1]
	v_pk_mul_f32 v[156:157], v[156:157], v[134:135]
	v_cvt_pk_bf16_f32 v167, v150, v151
	v_pk_mul_f32 v[152:153], v[156:157], v[152:153]
	v_pk_mul_f32 v[156:157], v[40:41], s[64:65] op_sel_hi:[1,0]
	v_cvt_pk_bf16_f32 v146, v152, v153
	v_exp_f32_e32 v156, v156
	v_exp_f32_e32 v157, v157
	v_lshlrev_b32_e32 v152, 16, v147
	v_and_b32_e32 v153, 0xffff0000, v147
	v_pk_mul_f32 v[152:153], v[154:155], v[152:153] op_sel_hi:[0,1]
	v_pk_add_f32 v[156:157], v[156:157], 1.0 op_sel_hi:[1,0]
	v_lshl_add_u64 v[150:151], s[20:21], 0, v[158:159]
	v_rcp_f32_e32 v156, v156
	v_rcp_f32_e32 v157, v157
	v_lshl_add_u64 v[150:151], v[150:151], 0, v[190:191]
	global_store_dwordx4 v[150:151], v[164:167], off
	v_pk_mul_f32 v[156:157], v[40:41], v[156:157]
	s_nop 0
	v_pk_mul_f32 v[156:157], v[156:157], v[136:137]
	s_nop 0
	v_pk_mul_f32 v[152:153], v[156:157], v[152:153]
	v_pk_mul_f32 v[156:157], v[34:35], s[64:65] op_sel_hi:[1,0]
	v_cvt_pk_bf16_f32 v147, v152, v153
	v_exp_f32_e32 v156, v156
	v_exp_f32_e32 v157, v157
	v_lshlrev_b32_e32 v152, 16, v148
	v_and_b32_e32 v153, 0xffff0000, v148
	v_pk_mul_f32 v[152:153], v[154:155], v[152:153] op_sel_hi:[0,1]
	v_pk_add_f32 v[156:157], v[156:157], 1.0 op_sel_hi:[1,0]
	s_nop 0
	v_rcp_f32_e32 v156, v156
	v_rcp_f32_e32 v157, v157
	s_nop 0
	v_pk_mul_f32 v[156:157], v[34:35], v[156:157]
	s_nop 0
	v_pk_mul_f32 v[156:157], v[156:157], v[130:131]
	s_nop 0
	v_pk_mul_f32 v[152:153], v[156:157], v[152:153]
	v_pk_mul_f32 v[156:157], v[36:37], s[64:65] op_sel_hi:[1,0]
	v_cvt_pk_bf16_f32 v148, v152, v153
	v_exp_f32_e32 v156, v156
	v_exp_f32_e32 v157, v157
	v_lshlrev_b32_e32 v152, 16, v149
	v_and_b32_e32 v153, 0xffff0000, v149
	v_pk_mul_f32 v[152:153], v[154:155], v[152:153] op_sel_hi:[0,1]
	v_pk_add_f32 v[156:157], v[156:157], 1.0 op_sel_hi:[1,0]
	s_nop 0
	v_rcp_f32_e32 v156, v156
	v_rcp_f32_e32 v157, v157
	s_nop 0
	v_pk_mul_f32 v[156:157], v[36:37], v[156:157]
	s_nop 0
	v_pk_mul_f32 v[154:155], v[156:157], v[132:133]
	s_nop 0
	v_pk_mul_f32 v[152:153], v[154:155], v[152:153]
	s_nop 0
	v_cvt_pk_bf16_f32 v149, v152, v153
	global_store_dwordx4 v[150:151], v[146:149], off offset:256
	s_waitcnt vmcnt(4)
	v_fmamk_f32 v160, v242, 0x3b800000, v229
	v_add_u32_e32 v146, 0xa0, v186
	v_ashrrev_i32_e32 v147, 31, v146
	v_lshlrev_b64 v[164:165], 12, v[146:147]
	v_lshl_add_u64 v[146:147], v[200:201], 0, v[164:165]
	global_load_dwordx4 v[166:169], v[146:147], off
	global_load_dwordx4 v[154:157], v[146:147], off offset:256
	v_mov_b32_e32 v161, v243
	v_rsq_f32_e32 v160, v160
	v_add_u32_e32 v146, 0xb0, v186
	v_ashrrev_i32_e32 v147, 31, v146
	v_lshlrev_b64 v[158:159], 12, v[146:147]
	v_lshl_add_u64 v[146:147], v[200:201], 0, v[158:159]
	global_load_dwordx4 v[150:153], v[146:147], off
	s_nop 0
	global_load_dwordx4 v[146:149], v[146:147], off offset:256
	s_waitcnt vmcnt(3)
	v_lshlrev_b32_e32 v162, 16, v166
	v_and_b32_e32 v163, 0xffff0000, v166
	s_waitcnt vmcnt(2)
	v_pk_mul_f32 v[162:163], v[160:161], v[162:163] op_sel_hi:[0,1]
	v_pk_mul_f32 v[162:163], v[170:171], v[162:163]
	v_pk_mul_f32 v[170:171], v[32:33], s[64:65] op_sel_hi:[1,0]
	v_cvt_pk_bf16_f32 v166, v162, v163
	v_exp_f32_e32 v170, v170
	v_exp_f32_e32 v171, v171
	v_lshlrev_b32_e32 v162, 16, v167
	v_and_b32_e32 v163, 0xffff0000, v167
	v_pk_mul_f32 v[162:163], v[160:161], v[162:163] op_sel_hi:[0,1]
	v_pk_add_f32 v[170:171], v[170:171], 1.0 op_sel_hi:[1,0]
	s_nop 0
	v_rcp_f32_e32 v170, v170
	v_rcp_f32_e32 v171, v171
	s_nop 0
	v_pk_mul_f32 v[170:171], v[32:33], v[170:171]
	s_nop 0
	v_pk_mul_f32 v[170:171], v[170:171], v[144:145]
	s_nop 0
	v_pk_mul_f32 v[162:163], v[170:171], v[162:163]
	v_pk_mul_f32 v[170:171], v[26:27], s[64:65] op_sel_hi:[1,0]
	v_cvt_pk_bf16_f32 v167, v162, v163
	v_exp_f32_e32 v170, v170
	v_exp_f32_e32 v171, v171
	v_lshlrev_b32_e32 v162, 16, v168
	v_and_b32_e32 v163, 0xffff0000, v168
	v_pk_mul_f32 v[162:163], v[160:161], v[162:163] op_sel_hi:[0,1]
	v_pk_add_f32 v[170:171], v[170:171], 1.0 op_sel_hi:[1,0]
	s_nop 0
	v_rcp_f32_e32 v170, v170
	v_rcp_f32_e32 v171, v171
	s_nop 0
	v_pk_mul_f32 v[170:171], v[26:27], v[170:171]
	s_nop 0
	v_pk_mul_f32 v[170:171], v[170:171], v[138:139]
	s_nop 0
	v_pk_mul_f32 v[162:163], v[170:171], v[162:163]
	v_pk_mul_f32 v[170:171], v[28:29], s[64:65] op_sel_hi:[1,0]
	v_cvt_pk_bf16_f32 v168, v162, v163
	v_exp_f32_e32 v170, v170
	v_exp_f32_e32 v171, v171
	v_lshlrev_b32_e32 v162, 16, v169
	v_and_b32_e32 v163, 0xffff0000, v169
	v_pk_mul_f32 v[162:163], v[160:161], v[162:163] op_sel_hi:[0,1]
	v_pk_add_f32 v[170:171], v[170:171], 1.0 op_sel_hi:[1,0]
	s_nop 0
	v_rcp_f32_e32 v170, v170
	v_rcp_f32_e32 v171, v171
	s_nop 0
	v_pk_mul_f32 v[170:171], v[28:29], v[170:171]
	s_nop 0
	v_pk_mul_f32 v[170:171], v[170:171], v[140:141]
	s_nop 0
	v_pk_mul_f32 v[162:163], v[170:171], v[162:163]
	s_nop 0
	v_cvt_pk_bf16_f32 v169, v162, v163
	v_lshl_add_u64 v[162:163], s[20:21], 0, v[164:165]
	v_lshl_add_u64 v[162:163], v[162:163], 0, v[190:191]
	global_store_dwordx4 v[162:163], v[166:169], off
	v_lshlrev_b32_e32 v164, 16, v154
	v_and_b32_e32 v165, 0xffff0000, v154
	v_pk_mul_f32 v[166:167], v[22:23], s[64:65] op_sel_hi:[1,0]
	v_pk_mul_f32 v[164:165], v[160:161], v[164:165] op_sel_hi:[0,1]
	v_exp_f32_e32 v166, v166
	v_exp_f32_e32 v167, v167
	s_nop 0
	v_pk_add_f32 v[166:167], v[166:167], 1.0 op_sel_hi:[1,0]
	s_nop 0
	v_rcp_f32_e32 v166, v166
	v_rcp_f32_e32 v167, v167
	s_nop 0
	v_pk_mul_f32 v[166:167], v[22:23], v[166:167]
	s_nop 0
	v_pk_mul_f32 v[166:167], v[166:167], v[134:135]
	s_nop 0
	v_pk_mul_f32 v[164:165], v[166:167], v[164:165]
	v_pk_mul_f32 v[166:167], v[24:25], s[64:65] op_sel_hi:[1,0]
	v_cvt_pk_bf16_f32 v154, v164, v165
	v_exp_f32_e32 v166, v166
	v_exp_f32_e32 v167, v167
	v_lshlrev_b32_e32 v164, 16, v155
	v_and_b32_e32 v165, 0xffff0000, v155
	v_pk_mul_f32 v[164:165], v[160:161], v[164:165] op_sel_hi:[0,1]
	v_pk_add_f32 v[166:167], v[166:167], 1.0 op_sel_hi:[1,0]
	s_nop 0
	v_rcp_f32_e32 v166, v166
	v_rcp_f32_e32 v167, v167
	s_nop 0
	v_pk_mul_f32 v[166:167], v[24:25], v[166:167]
	s_nop 0
	v_pk_mul_f32 v[166:167], v[166:167], v[136:137]
	s_nop 0
	v_pk_mul_f32 v[164:165], v[166:167], v[164:165]
	v_pk_mul_f32 v[166:167], v[18:19], s[64:65] op_sel_hi:[1,0]
	v_cvt_pk_bf16_f32 v155, v164, v165
	v_exp_f32_e32 v166, v166
	v_exp_f32_e32 v167, v167
	v_lshlrev_b32_e32 v164, 16, v156
	v_and_b32_e32 v165, 0xffff0000, v156
	v_pk_mul_f32 v[164:165], v[160:161], v[164:165] op_sel_hi:[0,1]
	v_pk_add_f32 v[166:167], v[166:167], 1.0 op_sel_hi:[1,0]
	s_nop 0
	v_rcp_f32_e32 v166, v166
	v_rcp_f32_e32 v167, v167
	s_nop 0
	v_pk_mul_f32 v[166:167], v[18:19], v[166:167]
	s_nop 0
	v_pk_mul_f32 v[166:167], v[166:167], v[130:131]
	s_nop 0
	v_pk_mul_f32 v[164:165], v[166:167], v[164:165]
	v_pk_mul_f32 v[166:167], v[20:21], s[64:65] op_sel_hi:[1,0]
	v_cvt_pk_bf16_f32 v156, v164, v165
	v_exp_f32_e32 v166, v166
	v_exp_f32_e32 v167, v167
	v_lshlrev_b32_e32 v164, 16, v157
	v_and_b32_e32 v165, 0xffff0000, v157
	v_pk_mul_f32 v[164:165], v[160:161], v[164:165] op_sel_hi:[0,1]
	v_pk_add_f32 v[166:167], v[166:167], 1.0 op_sel_hi:[1,0]
	s_nop 0
	v_rcp_f32_e32 v166, v166
	v_rcp_f32_e32 v167, v167
	s_nop 0
	v_pk_mul_f32 v[166:167], v[20:21], v[166:167]
	s_nop 0
	v_pk_mul_f32 v[166:167], v[166:167], v[132:133]
	s_nop 0
	v_pk_mul_f32 v[164:165], v[166:167], v[164:165]
	s_nop 0
	v_cvt_pk_bf16_f32 v157, v164, v165
	global_store_dwordx4 v[162:163], v[154:157], off offset:256
	s_nop 1
	v_fmamk_f32 v154, v161, 0x3b800000, v229
	v_pk_mul_f32 v[160:161], v[14:15], s[64:65] op_sel_hi:[1,0]
	v_rsq_f32_e32 v154, v154
	v_exp_f32_e32 v160, v160
	v_exp_f32_e32 v161, v161
	s_waitcnt vmcnt(3)
	v_lshlrev_b32_e32 v156, 16, v150
	v_and_b32_e32 v157, 0xffff0000, v150
	v_pk_mul_f32 v[156:157], v[154:155], v[156:157] op_sel_hi:[0,1]
	v_pk_add_f32 v[160:161], v[160:161], 1.0 op_sel_hi:[1,0]
	v_lshlrev_b32_e32 v150, 16, v151
	v_rcp_f32_e32 v160, v160
	v_rcp_f32_e32 v161, v161
	v_and_b32_e32 v151, 0xffff0000, v151
	v_pk_mul_f32 v[150:151], v[154:155], v[150:151] op_sel_hi:[0,1]
	v_pk_mul_f32 v[160:161], v[14:15], v[160:161]
	s_nop 0
	v_pk_mul_f32 v[142:143], v[160:161], v[142:143]
	s_nop 0
	v_pk_mul_f32 v[142:143], v[142:143], v[156:157]
	v_pk_mul_f32 v[156:157], v[16:17], s[64:65] op_sel_hi:[1,0]
	v_cvt_pk_bf16_f32 v142, v142, v143
	v_exp_f32_e32 v156, v156
	v_exp_f32_e32 v157, v157
	s_nop 0
	v_pk_add_f32 v[156:157], v[156:157], 1.0 op_sel_hi:[1,0]
	s_nop 0
	v_rcp_f32_e32 v156, v156
	v_rcp_f32_e32 v157, v157
	s_nop 0
	v_pk_mul_f32 v[156:157], v[16:17], v[156:157]
	s_nop 0
	v_pk_mul_f32 v[144:145], v[156:157], v[144:145]
	s_nop 0
	v_pk_mul_f32 v[144:145], v[144:145], v[150:151]
	v_pk_mul_f32 v[150:151], v[10:11], s[64:65] op_sel_hi:[1,0]
	v_cvt_pk_bf16_f32 v143, v144, v145
	v_exp_f32_e32 v150, v150
	v_exp_f32_e32 v151, v151
	v_lshlrev_b32_e32 v144, 16, v152
	v_and_b32_e32 v145, 0xffff0000, v152
	v_pk_mul_f32 v[144:145], v[154:155], v[144:145] op_sel_hi:[0,1]
	v_pk_add_f32 v[150:151], v[150:151], 1.0 op_sel_hi:[1,0]
	s_nop 0
	v_rcp_f32_e32 v150, v150
	v_rcp_f32_e32 v151, v151
	s_nop 0
	v_pk_mul_f32 v[150:151], v[10:11], v[150:151]
	s_nop 0
	v_pk_mul_f32 v[138:139], v[150:151], v[138:139]
	v_pk_mul_f32 v[150:151], v[12:13], s[64:65] op_sel_hi:[1,0]
	v_pk_mul_f32 v[138:139], v[138:139], v[144:145]
	v_exp_f32_e32 v150, v150
	v_exp_f32_e32 v151, v151
	v_cvt_pk_bf16_f32 v144, v138, v139
	v_lshlrev_b32_e32 v138, 16, v153
	v_and_b32_e32 v139, 0xffff0000, v153
	v_pk_add_f32 v[150:151], v[150:151], 1.0 op_sel_hi:[1,0]
	v_pk_mul_f32 v[138:139], v[154:155], v[138:139] op_sel_hi:[0,1]
	v_rcp_f32_e32 v150, v150
	v_rcp_f32_e32 v151, v151
	s_nop 0
	v_pk_mul_f32 v[150:151], v[12:13], v[150:151]
	s_nop 0
	v_pk_mul_f32 v[140:141], v[150:151], v[140:141]
	s_nop 0
	v_pk_mul_f32 v[138:139], v[140:141], v[138:139]
	s_waitcnt vmcnt(2)
	v_lshlrev_b32_e32 v140, 16, v146
	v_cvt_pk_bf16_f32 v145, v138, v139
	v_lshl_add_u64 v[138:139], s[20:21], 0, v[158:159]
	v_lshl_add_u64 v[138:139], v[138:139], 0, v[190:191]
	global_store_dwordx4 v[138:139], v[142:145], off
	v_and_b32_e32 v141, 0xffff0000, v146
	v_pk_mul_f32 v[140:141], v[154:155], v[140:141] op_sel_hi:[0,1]
	v_pk_mul_f32 v[142:143], v[6:7], s[64:65] op_sel_hi:[1,0]
	s_nop 0
	v_exp_f32_e32 v142, v142
	v_exp_f32_e32 v143, v143
	s_nop 0
	v_pk_add_f32 v[142:143], v[142:143], 1.0 op_sel_hi:[1,0]
	s_nop 0
	v_rcp_f32_e32 v142, v142
	v_rcp_f32_e32 v143, v143
	s_nop 0
	v_pk_mul_f32 v[142:143], v[6:7], v[142:143]
	s_nop 0
	v_pk_mul_f32 v[134:135], v[142:143], v[134:135]
	v_pk_mul_f32 v[142:143], v[8:9], s[64:65] op_sel_hi:[1,0]
	v_pk_mul_f32 v[134:135], v[134:135], v[140:141]
	v_exp_f32_e32 v142, v142
	v_exp_f32_e32 v143, v143
	v_lshlrev_b32_e32 v140, 16, v147
	v_and_b32_e32 v141, 0xffff0000, v147
	v_pk_mul_f32 v[140:141], v[154:155], v[140:141] op_sel_hi:[0,1]
	v_pk_add_f32 v[142:143], v[142:143], 1.0 op_sel_hi:[1,0]
	v_cvt_pk_bf16_f32 v134, v134, v135
	v_rcp_f32_e32 v142, v142
	v_rcp_f32_e32 v143, v143
	s_nop 0
	v_pk_mul_f32 v[142:143], v[8:9], v[142:143]
	s_nop 0
	v_pk_mul_f32 v[136:137], v[142:143], v[136:137]
	s_nop 0
	v_pk_mul_f32 v[136:137], v[136:137], v[140:141]
	v_pk_mul_f32 v[140:141], v[2:3], s[64:65] op_sel_hi:[1,0]
	v_cvt_pk_bf16_f32 v135, v136, v137
	v_exp_f32_e32 v140, v140
	v_exp_f32_e32 v141, v141
	v_lshlrev_b32_e32 v136, 16, v148
	v_and_b32_e32 v137, 0xffff0000, v148
	v_pk_mul_f32 v[136:137], v[154:155], v[136:137] op_sel_hi:[0,1]
	v_pk_add_f32 v[140:141], v[140:141], 1.0 op_sel_hi:[1,0]
	s_nop 0
	v_rcp_f32_e32 v140, v140
	v_rcp_f32_e32 v141, v141
	s_nop 0
	v_pk_mul_f32 v[140:141], v[2:3], v[140:141]
	s_nop 0
	v_pk_mul_f32 v[130:131], v[140:141], v[130:131]
	v_pk_mul_f32 v[140:141], v[4:5], s[64:65] op_sel_hi:[1,0]
	v_pk_mul_f32 v[130:131], v[130:131], v[136:137]
	v_exp_f32_e32 v140, v140
	v_exp_f32_e32 v141, v141
	v_cvt_pk_bf16_f32 v136, v130, v131
	v_lshlrev_b32_e32 v130, 16, v149
	v_and_b32_e32 v131, 0xffff0000, v149
	v_pk_add_f32 v[140:141], v[140:141], 1.0 op_sel_hi:[1,0]
	v_pk_mul_f32 v[130:131], v[154:155], v[130:131] op_sel_hi:[0,1]
	v_rcp_f32_e32 v140, v140
	v_rcp_f32_e32 v141, v141
	s_nop 0
	v_pk_mul_f32 v[140:141], v[4:5], v[140:141]
	s_nop 0
	v_pk_mul_f32 v[132:133], v[140:141], v[132:133]
	s_nop 0
	v_pk_mul_f32 v[130:131], v[132:133], v[130:131]
	s_nop 0
	v_cvt_pk_bf16_f32 v137, v130, v131
	global_store_dwordx4 v[138:139], v[134:137], off offset:256
